# PREP tail units (1024..1031) moved into SCAN phase on idle vblocks with release/acquire flag; PREP now exactly 2 rounds
# speedup vs baseline: 1.0628x; 1.0628x over previous
; __device__ __forceinline__ void run_phase(CP p, int ph, char* smem_full) {
;     ...
;       for (int u = vb; u < NB * 129; u += NVB) prep_unit(p, l, u, smem);
;     } break;
;     case 3: {
;       for (int u = vb; u < 320; u += NVB) {
;         if (u < 128) { for (int rr_ = 0; rr_ < ((SCAN_REP >> 0) & 1) + 1; ++rr_) rwkv_scan_unit(p, u, smem); }
;         else if (u < 256) { for (int rr_ = 0; rr_ < ((SCAN_REP >> 1) & 1) + 1; ++rr_) ssd_scan_unit(p, l, u - 128, smem); }
;         else if (u < 272) ret_mfma_unit(p, l, u - 256, smem);
;         else if (u < 288) { }
;         else if (u < 320) { for (int rr_ = 0; rr_ < ((SCAN_REP >> 3) & 1) + 1; ++rr_) lru_scan_unit(p, u - 288, smem); }
;       }
.Lmap_a:
	s_cmpk_lt_i32 s0, 0x78
	s_cbranch_scc0 .Lmap_a2
	s_add_i32 s54, s0, 0x390
	s_branch .Lprep_entry

; __device__ __forceinline__ int tidx() { int t = threadIdx.x & 255; asm volatile("" : "+v"(t)); return t; }
; __device__ __forceinline__ int half_id() { int t = (int)(threadIdx.x >> 8); asm volatile("" : "+v"(t)); return __builtin_amdgcn_readfirstlane(t); }
; #define LAS3 __attribute__((address_space(3)))
; __device__ __forceinline__ void half_barrier(char* smem_half) {
;   const int h = half_id();
;   LAS3 unsigned* cnt = (LAS3 unsigned*)(smem_half + (2 - h) * 65536 + 8 + h * 4);
;   asm volatile("s_waitcnt lgkmcnt(0)" ::: "memory");
;   if ((tidx() & 63) == 0) {
;     const unsigned old = __hip_atomic_fetch_add(cnt, 1u, __ATOMIC_RELAXED, __HIP_MEMORY_SCOPE_WORKGROUP);
;     const unsigned target = (old & ~3u) + 4u;
;     while (__hip_atomic_load(cnt, __ATOMIC_RELAXED, __HIP_MEMORY_SCOPE_WORKGROUP) < target) __builtin_amdgcn_s_sleep(1);
;   }
; __device__ __forceinline__ void run_phase(CP p, int ph, char* smem_full) {
;     ...
;       for (int u = vb; u < 320; u += NVB) {
;         if (u < 128) { for (int rr_ = 0; rr_ < ((SCAN_REP >> 0) & 1) + 1; ++rr_) rwkv_scan_unit(p, u, smem); }
;         else if (u < 256) { for (int rr_ = 0; rr_ < ((SCAN_REP >> 1) & 1) + 1; ++rr_) ssd_scan_unit(p, l, u - 128, smem); }
;         else if (u < 272) ret_mfma_unit(p, l, u - 256, smem);
;         else if (u < 288) { }
;         else if (u < 320) { for (int rr_ = 0; rr_ < ((SCAN_REP >> 3) & 1) + 1; ++rr_) lru_scan_unit(p, u - 288, smem); }
.LBB0_395:
	s_cmpk_gt_i32 s57, 0x7f
	s_mov_b64 s[2:3], -1
	s_movk_i32 s0, 0x1000
	s_cbranch_scc0 .LBB0_559
	s_mov_b32 s59, s54
	s_cmpk_gt_u32 s57, 0xff
	s_mov_b32 s40, 0x3fb8aa3b
	s_mov_b32 s41, 0x3f200000
	s_mov_b32 s54, 0xc2ce8ed0
	s_mov_b32 s55, 0x42b17218
	s_brev_b32 s58, -2
	s_cbranch_scc0 .LBB0_527
	s_cmpk_gt_u32 s57, 0x10f
	s_cbranch_scc0 .LBB0_517
	s_cmpk_lt_u32 s57, 0x120
	s_cbranch_scc1 .LBB0_516
	s_cmpk_lt_u32 s57, 0x13c
	s_cbranch_scc1 .Ltw_donelr
	v_readlane_b32 s2, v254, 12
	s_mov_b32 s3, 0
	s_add_i32 s2, s2, 1
	s_lshl_b32 s2, s2, 5
.Ltw_spinlr:
	global_load_dword v0, v149, s[52:53] sc1
	s_waitcnt vmcnt(0)
	v_readfirstlane_b32 s5, v0
	s_add_i32 s3, s3, 1
	s_cmp_ge_u32 s5, s2
	s_cbranch_scc1 .Ltw_oklr
	s_cmpk_gt_u32 s3, 0x800
	s_cbranch_scc1 .Ltw_oklr
	s_sleep 16
	s_branch .Ltw_spinlr
.Ltw_oklr:
	buffer_inv sc1
	s_waitcnt vmcnt(0)
.Ltw_donelr:
	s_waitcnt vmcnt(1)
	v_mov_b32_e32 v54, v214
	v_mov_b32_e32 v0, v213
	s_waitcnt lgkmcnt(0)
	s_nop 0
	v_readfirstlane_b32 s11, v0
	v_mov_b32_e32 v0, v214
	s_nop 0
	v_and_b32_e32 v0, 63, v0
	v_cmp_eq_u32_e32 vcc, 0, v0
	s_and_saveexec_b64 s[2:3], vcc
	s_cbranch_execz .LBB0_405
	s_mov_b64 s[4:5], exec
	s_lshl_b32 s10, s11, 16
	v_mbcnt_lo_u32_b32 v0, s4, 0
	s_sub_i32 s10, s63, s10
	v_mbcnt_hi_u32_b32 v0, s5, v0
	s_add_i32 s10, s10, 0x20000
	s_lshl_b32 s11, s11, 2
	v_cmp_eq_u32_e32 vcc, 0, v0
	s_and_saveexec_b64 s[12:13], vcc
	s_bcnt1_i32_b64 s4, s[4:5]
	s_add_i32 s5, s10, s11
	v_mov_b32_e32 v1, s5
	v_mov_b32_e32 v2, s4
	ds_add_rtn_u32 v1, v1, v2 offset:8
	s_or_b64 exec, exec, s[12:13]
	s_add_i32 s10, s10, s11
	s_waitcnt lgkmcnt(0)
	v_readfirstlane_b32 s4, v1
	v_mov_b32_e32 v1, s10
	ds_read_b32 v1, v1 offset:8
	v_add_u32_e32 v0, s4, v0
	v_and_b32_e32 v0, -4, v0
	v_add_u32_e32 v0, 4, v0
	s_waitcnt lgkmcnt(0)
	v_cmp_lt_u32_e32 vcc, v1, v0
	s_and_b64 exec, exec, vcc
	s_cbranch_execz .LBB0_405
	s_mov_b64 s[4:5], 0

; __device__ __forceinline__ void ssd_scan_unit(CP p, int l, int u, char* smem) {
;     ...
;   for (int c = 0; c < NCH; ++c) {
;     if (c + 1 < NCH) gload(c + 1);
;     const float* cb = buf + (c & 1) * 16 * SST;
;     float ykeep = 0.f;
;     float4 B0 = *reinterpret_cast<const float4*>(cb + j * 4), B1 = *reinterpret_cast<const float4*>(cb + 64 + j * 4);
;     float4 C0 = *reinterpret_cast<const float4*>(cb + 128 + j * 4), C1 = *reinterpret_cast<const float4*>(cb + 192 + j * 4);
;     float xdt = cb[256 + prow], xr = cb[272 + prow], a = cb[288];
; #pragma unroll 2
;     for (int s = 0; s < 16; ++s) {
;       const float* sb = cb + (s + 1) * SST;
;       const float4 B0n = *reinterpret_cast<const float4*>(sb + j * 4), B1n = *reinterpret_cast<const float4*>(sb + 64 + j * 4);
;       const float4 C0n = *reinterpret_cast<const float4*>(sb + 128 + j * 4), C1n = *reinterpret_cast<const float4*>(sb + 192 + j * 4);
;       const float xdtn = sb[256 + prow], xrn = sb[272 + prow], an = sb[288];
;       __builtin_amdgcn_sched_barrier(0);
.Lsd_head:
	s_add_i32 s28, s4, 1
	s_cmpk_lg_i32 s4, 100
	s_cbranch_scc1 .Ltw_donesd
	s_cmpk_lt_i32 s57, 240
	s_cbranch_scc1 .Ltw_donesd
	v_readlane_b32 s2, v254, 12
	s_mov_b32 s3, 0
	s_add_i32 s2, s2, 1
	s_lshl_b32 s2, s2, 5
.Ltw_spinsd:
	global_load_dword v196, v149, s[52:53] sc1
	s_waitcnt vmcnt(0)
	v_readfirstlane_b32 s5, v196
	s_add_i32 s3, s3, 1
	s_cmp_ge_u32 s5, s2
	s_cbranch_scc1 .Ltw_oksd
	s_cmpk_gt_u32 s3, 0x800
	s_cbranch_scc1 .Ltw_oksd
	s_sleep 16
	s_branch .Ltw_spinsd

; __device__ __forceinline__ void ssd_scan_unit(CP p, int l, int u, char* smem) {
;     ...
;   for (int c = 0; c < NCH; ++c) {
;     if (c + 1 < NCH) gload(c + 1);
;     const float* cb = buf + (c & 1) * 16 * SST;
;     float ykeep = 0.f;
;     float4 B0 = *reinterpret_cast<const float4*>(cb + j * 4), B1 = *reinterpret_cast<const float4*>(cb + 64 + j * 4);
;     float4 C0 = *reinterpret_cast<const float4*>(cb + 128 + j * 4), C1 = *reinterpret_cast<const float4*>(cb + 192 + j * 4);
;     float xdt = cb[256 + prow], xr = cb[272 + prow], a = cb[288];
; #pragma unroll 2
;     for (int s = 0; s < 16; ++s) {
;       const float* sb = cb + (s + 1) * SST;
;       const float4 B0n = *reinterpret_cast<const float4*>(sb + j * 4), B1n = *reinterpret_cast<const float4*>(sb + 64 + j * 4);
;       const float4 C0n = *reinterpret_cast<const float4*>(sb + 128 + j * 4), C1n = *reinterpret_cast<const float4*>(sb + 192 + j * 4);
;       const float xdtn = sb[256 + prow], xrn = sb[272 + prow], an = sb[288];
;       __builtin_amdgcn_sched_barrier(0);
;       hs[0] = fmaf(a, hs[0], xdt * B0.x); hs[1] = fmaf(a, hs[1], xdt * B0.y); hs[2] = fmaf(a, hs[2], xdt * B0.z); hs[3] = fmaf(a, hs[3], xdt * B0.w);
;       hs[4] = fmaf(a, hs[4], xdt * B1.x); hs[5] = fmaf(a, hs[5], xdt * B1.y); hs[6] = fmaf(a, hs[6], xdt * B1.z); hs[7] = fmaf(a, hs[7], xdt * B1.w);
;       float y = hs[0] * C0.x + hs[1] * C0.y + hs[2] * C0.z + hs[3] * C0.w + hs[4] * C1.x + hs[5] * C1.y + hs[6] * C1.z + hs[7] * C1.w;
;       y = allreduce16(y);
;       y = fmaf(Dh, xr, y);
;       if (j == s) ykeep = y;
;       B0 = B0n; B1 = B1n; C0 = C0n; C1 = C1n; xdt = xdtn; xr = xrn; a = an;
;     }
.Ltw_donesd:
	s_bitcmp1_b32 s4, 0
	s_cselect_b32 s12, 0x4a00, 0
	s_cselect_b32 s13, 0x80, 0
	s_cselect_b32 s5, 0x400, 0
	s_add_i32 s12, s63, s12
	s_add_i32 s13, s63, s13
	s_add_i32 s5, s63, s5
	v_lshl_add_u32 v84, v56, 2, s12
	v_add_u32_e32 v85, s12, v82
	v_mov_b32_e32 v86, s13
	v_add_u32_e32 v87, s5, v81
	ds_read_b128 v[106:109], v85 offset:1024
	ds_read_b128 v[134:137], v86 offset:37888
	ds_read_b128 v[128:131], v85 offset:1040
	ds_read_b128 v[138:141], v86 offset:37904
	ds_read_b128 v[90:93], v84 offset:0
	ds_read_b128 v[94:97], v84 offset:256
	ds_read_b128 v[98:101], v84 offset:512
	ds_read_b128 v[102:105], v84 offset:768
	ds_read_b128 v[112:115], v84 offset:1184
	ds_read_b128 v[116:119], v84 offset:1440
	ds_read_b128 v[120:123], v84 offset:1696
	ds_read_b128 v[124:127], v84 offset:1952
	ds_read_b32 v186, v87 offset:38912
	s_waitcnt lgkmcnt(7)
	v_pk_mul_f32 v[176:177], v[90:91], v[106:107]
	v_pk_mul_f32 v[178:179], v[92:93], v[106:107]
	v_pk_mul_f32 v[180:181], v[94:95], v[106:107]
	v_pk_mul_f32 v[182:183], v[96:97], v[106:107]
	ds_read_b128 v[90:93], v84 offset:2368
	ds_read_b128 v[94:97], v84 offset:2624
	s_waitcnt lgkmcnt(5)
	v_pk_fma_f32 v[32:33], v[134:135], v[32:33], v[176:177]
	v_pk_fma_f32 v[38:39], v[134:135], v[38:39], v[178:179]
	v_pk_fma_f32 v[36:37], v[134:135], v[36:37], v[180:181]
	v_pk_fma_f32 v[34:35], v[134:135], v[34:35], v[182:183]
	v_pk_mul_f32 v[184:185], v[32:33], v[98:99]
	v_pk_mul_f32 v[176:177], v[112:113], v[108:109]
	v_pk_fma_f32 v[184:185], v[38:39], v[100:101], v[184:185]
	v_pk_mul_f32 v[178:179], v[114:115], v[108:109]
	v_pk_fma_f32 v[184:185], v[36:37], v[102:103], v[184:185]
	v_pk_mul_f32 v[180:181], v[116:117], v[108:109]
	v_pk_fma_f32 v[184:185], v[34:35], v[104:105], v[184:185]
	v_pk_mul_f32 v[182:183], v[118:119], v[108:109]
	v_add_f32_e32 v160, v184, v185
	ds_read_b128 v[112:115], v84 offset:3552
	ds_read_b128 v[116:119], v84 offset:3808
	ds_read_b128 v[98:101], v84 offset:2880
	ds_read_b128 v[102:105], v84 offset:3136
	ds_read_b128 v[106:109], v85 offset:1056
	s_waitcnt lgkmcnt(5)
	v_pk_fma_f32 v[32:33], v[136:137], v[32:33], v[176:177]
	v_pk_fma_f32 v[38:39], v[136:137], v[38:39], v[178:179]
	v_pk_fma_f32 v[36:37], v[136:137], v[36:37], v[180:181]
	v_pk_fma_f32 v[34:35], v[136:137], v[34:35], v[182:183]
	v_pk_mul_f32 v[184:185], v[32:33], v[120:121]
	v_pk_mul_f32 v[176:177], v[90:91], v[128:129]
	v_pk_fma_f32 v[184:185], v[38:39], v[122:123], v[184:185]
	v_pk_mul_f32 v[178:179], v[92:93], v[128:129]
	v_pk_fma_f32 v[184:185], v[36:37], v[124:125], v[184:185]
	v_pk_mul_f32 v[180:181], v[94:95], v[128:129]
	v_pk_fma_f32 v[184:185], v[34:35], v[126:127], v[184:185]
	v_pk_mul_f32 v[182:183], v[96:97], v[128:129]
	v_add_f32_e32 v161, v184, v185
	ds_read_b128 v[90:93], v84 offset:4736
	ds_read_b128 v[94:97], v84 offset:4992
	ds_read_b128 v[120:123], v84 offset:4064
	ds_read_b128 v[124:127], v84 offset:4320
	ds_read_b128 v[134:137], v86 offset:37920
	s_waitcnt lgkmcnt(6)
	v_pk_fma_f32 v[32:33], v[138:139], v[32:33], v[176:177]
	v_pk_fma_f32 v[38:39], v[138:139], v[38:39], v[178:179]
	v_pk_fma_f32 v[36:37], v[138:139], v[36:37], v[180:181]
	v_pk_fma_f32 v[34:35], v[138:139], v[34:35], v[182:183]
	v_pk_mul_f32 v[184:185], v[32:33], v[98:99]
	v_pk_mul_f32 v[176:177], v[112:113], v[130:131]
	v_pk_fma_f32 v[184:185], v[38:39], v[100:101], v[184:185]
	v_pk_mul_f32 v[178:179], v[114:115], v[130:131]
	v_pk_fma_f32 v[184:185], v[36:37], v[102:103], v[184:185]
	v_pk_mul_f32 v[180:181], v[116:117], v[130:131]
	v_pk_fma_f32 v[184:185], v[34:35], v[104:105], v[184:185]
	v_pk_mul_f32 v[182:183], v[118:119], v[130:131]
	v_add_f32_e32 v162, v184, v185
	ds_read_b128 v[112:115], v84 offset:5920
	ds_read_b128 v[116:119], v84 offset:6176
	ds_read_b128 v[98:101], v84 offset:5248
	ds_read_b128 v[102:105], v84 offset:5504
	ds_read_b128 v[128:131], v85 offset:1072
	s_waitcnt lgkmcnt(6)
	v_pk_fma_f32 v[32:33], v[140:141], v[32:33], v[176:177]
	v_pk_fma_f32 v[38:39], v[140:141], v[38:39], v[178:179]
	v_pk_fma_f32 v[36:37], v[140:141], v[36:37], v[180:181]
	v_pk_fma_f32 v[34:35], v[140:141], v[34:35], v[182:183]
	v_pk_mul_f32 v[184:185], v[32:33], v[120:121]
	v_pk_mul_f32 v[176:177], v[90:91], v[106:107]
	v_pk_fma_f32 v[184:185], v[38:39], v[122:123], v[184:185]
	v_pk_mul_f32 v[178:179], v[92:93], v[106:107]
	v_pk_fma_f32 v[184:185], v[36:37], v[124:125], v[184:185]
	v_pk_mul_f32 v[180:181], v[94:95], v[106:107]
	v_pk_fma_f32 v[184:185], v[34:35], v[126:127], v[184:185]
	v_pk_mul_f32 v[182:183], v[96:97], v[106:107]
	v_add_f32_e32 v163, v184, v185
	ds_read_b128 v[90:93], v84 offset:7104
	ds_read_b128 v[94:97], v84 offset:7360
	ds_read_b128 v[120:123], v84 offset:6432
	ds_read_b128 v[124:127], v84 offset:6688
	ds_read_b128 v[138:141], v86 offset:37936
	s_waitcnt lgkmcnt(6)
; __device__ __forceinline__ void ssd_scan_unit(CP p, int l, int u, char* smem) {
;     ...
;   auto gload = [&](int c) {
;     const int rb = rowof(b, c * 16);
; #pragma unroll
;     for (int x = 0; x < 2; ++x) {
;       const int e = tid + x * 256, tok = e >> 5, rem = e & 31, which = rem >> 4, part = rem & 15;
;       st[x] = *reinterpret_cast<const uint4*>(SS + (size_t)(rb + tok) * 768 + 256 + which * 256 + g * 128 + part * 8);
;     }
;     {
;       const int tok = tid >> 4, pp = tid & 15;
;       stxr = SS[(size_t)(rb + tok) * 768 + h * 64 + q * 16 + pp];
;       stdt = SD[(size_t)(rb + tok) * 4 + h];
;     }
;   };
;   auto lwrite = [&](int bi) {
; #pragma unroll
;     for (int x = 0; x < 2; ++x) {
;       const int e = tid + x * 256, tok = e >> 5, rem = e & 31, which = rem >> 4, part = rem & 15;
;       float* d = buf + bi * 16 * SST + tok * SST + which * 128 + part * 8;
;       *reinterpret_cast<float4*>(d) = make_float4(lo2f(st[x].x), hi2f(st[x].x), lo2f(st[x].y), hi2f(st[x].y));
;       *reinterpret_cast<float4*>(d + 4) = make_float4(lo2f(st[x].z), hi2f(st[x].z), lo2f(st[x].w), hi2f(st[x].w));
;     }
;     {
;       const int tok = tid >> 4, pp = tid & 15;
;     ...
;     for (int s = 0; s < 16; ++s) {
;       const float* sb = cb + (s + 1) * SST;
;       const float4 B0n = *reinterpret_cast<const float4*>(sb + j * 4), B1n = *reinterpret_cast<const float4*>(sb + 64 + j * 4);
;       const float4 C0n = *reinterpret_cast<const float4*>(sb + 128 + j * 4), C1n = *reinterpret_cast<const float4*>(sb + 192 + j * 4);
;       const float xdtn = sb[256 + prow], xrn = sb[272 + prow], an = sb[288];
;       __builtin_amdgcn_sched_barrier(0);
;       hs[0] = fmaf(a, hs[0], xdt * B0.x); hs[1] = fmaf(a, hs[1], xdt * B0.y); hs[2] = fmaf(a, hs[2], xdt * B0.z); hs[3] = fmaf(a, hs[3], xdt * B0.w);
;       hs[4] = fmaf(a, hs[4], xdt * B1.x); hs[5] = fmaf(a, hs[5], xdt * B1.y); hs[6] = fmaf(a, hs[6], xdt * B1.z); hs[7] = fmaf(a, hs[7], xdt * B1.w);
;       float y = hs[0] * C0.x + hs[1] * C0.y + hs[2] * C0.z + hs[3] * C0.w + hs[4] * C1.x + hs[5] * C1.y + hs[6] * C1.z + hs[7] * C1.w;
;       y = allreduce16(y);
;       y = fmaf(Dh, xr, y);
;       if (j == s) ykeep = y;
;       B0 = B0n; B1 = B1n; C0 = C0n; C1 = C1n; xdt = xdtn; xr = xrn; a = an;
;     }
;     Y[(size_t)(rowof(b, c * 16) + j) * 1024 + h * 64 + q * 16 + prow] = f2bf(ykeep);
;     if (c + 1 < NCH) lwrite((c + 1) & 1);
	v_pk_fma_f32 v[32:33], v[134:135], v[32:33], v[176:177]
	v_pk_fma_f32 v[38:39], v[134:135], v[38:39], v[178:179]
	v_pk_fma_f32 v[36:37], v[134:135], v[36:37], v[180:181]
	v_pk_fma_f32 v[34:35], v[134:135], v[34:35], v[182:183]
	v_pk_mul_f32 v[184:185], v[32:33], v[98:99]
	v_pk_mul_f32 v[176:177], v[112:113], v[108:109]
	v_pk_fma_f32 v[184:185], v[38:39], v[100:101], v[184:185]
	v_pk_mul_f32 v[178:179], v[114:115], v[108:109]
	v_pk_fma_f32 v[184:185], v[36:37], v[102:103], v[184:185]
	v_pk_mul_f32 v[180:181], v[116:117], v[108:109]
	v_pk_fma_f32 v[184:185], v[34:35], v[104:105], v[184:185]
	v_pk_mul_f32 v[182:183], v[118:119], v[108:109]
	v_add_f32_e32 v164, v184, v185
	ds_read_b128 v[112:115], v84 offset:8288
	ds_read_b128 v[116:119], v84 offset:8544
	ds_read_b128 v[98:101], v84 offset:7616
	ds_read_b128 v[102:105], v84 offset:7872
	ds_read_b128 v[106:109], v85 offset:1088
	s_waitcnt lgkmcnt(6)
	v_pk_fma_f32 v[32:33], v[136:137], v[32:33], v[176:177]
	v_pk_fma_f32 v[38:39], v[136:137], v[38:39], v[178:179]
	v_pk_fma_f32 v[36:37], v[136:137], v[36:37], v[180:181]
	v_pk_fma_f32 v[34:35], v[136:137], v[34:35], v[182:183]
	v_pk_mul_f32 v[184:185], v[32:33], v[120:121]
	v_pk_mul_f32 v[176:177], v[90:91], v[128:129]
	v_pk_fma_f32 v[184:185], v[38:39], v[122:123], v[184:185]
	v_pk_mul_f32 v[178:179], v[92:93], v[128:129]
	v_pk_fma_f32 v[184:185], v[36:37], v[124:125], v[184:185]
	v_pk_mul_f32 v[180:181], v[94:95], v[128:129]
	v_pk_fma_f32 v[184:185], v[34:35], v[126:127], v[184:185]
	v_pk_mul_f32 v[182:183], v[96:97], v[128:129]
	v_add_f32_e32 v165, v184, v185
	ds_read_b128 v[90:93], v84 offset:9472
	ds_read_b128 v[94:97], v84 offset:9728
	ds_read_b128 v[120:123], v84 offset:8800
	ds_read_b128 v[124:127], v84 offset:9056
	ds_read_b128 v[134:137], v86 offset:37952
	s_waitcnt lgkmcnt(6)
	v_pk_fma_f32 v[32:33], v[138:139], v[32:33], v[176:177]
	v_pk_fma_f32 v[38:39], v[138:139], v[38:39], v[178:179]
	v_pk_fma_f32 v[36:37], v[138:139], v[36:37], v[180:181]
	v_pk_fma_f32 v[34:35], v[138:139], v[34:35], v[182:183]
	v_pk_mul_f32 v[184:185], v[32:33], v[98:99]
	v_pk_mul_f32 v[176:177], v[112:113], v[130:131]
	v_pk_fma_f32 v[184:185], v[38:39], v[100:101], v[184:185]
	v_pk_mul_f32 v[178:179], v[114:115], v[130:131]
	v_pk_fma_f32 v[184:185], v[36:37], v[102:103], v[184:185]
	v_pk_mul_f32 v[180:181], v[116:117], v[130:131]
	v_pk_fma_f32 v[184:185], v[34:35], v[104:105], v[184:185]
	v_pk_mul_f32 v[182:183], v[118:119], v[130:131]
	v_add_f32_e32 v166, v184, v185
	ds_read_b128 v[112:115], v84 offset:10656
	ds_read_b128 v[116:119], v84 offset:10912
	ds_read_b128 v[98:101], v84 offset:9984
	ds_read_b128 v[102:105], v84 offset:10240
	ds_read_b128 v[128:131], v85 offset:1104
	s_waitcnt lgkmcnt(6)
	v_pk_fma_f32 v[32:33], v[140:141], v[32:33], v[176:177]
	v_pk_fma_f32 v[38:39], v[140:141], v[38:39], v[178:179]
	v_pk_fma_f32 v[36:37], v[140:141], v[36:37], v[180:181]
	v_pk_fma_f32 v[34:35], v[140:141], v[34:35], v[182:183]
	v_pk_mul_f32 v[184:185], v[32:33], v[120:121]
	v_pk_mul_f32 v[176:177], v[90:91], v[106:107]
	v_pk_fma_f32 v[184:185], v[38:39], v[122:123], v[184:185]
	v_pk_mul_f32 v[178:179], v[92:93], v[106:107]
	v_pk_fma_f32 v[184:185], v[36:37], v[124:125], v[184:185]
	v_pk_mul_f32 v[180:181], v[94:95], v[106:107]
	v_pk_fma_f32 v[184:185], v[34:35], v[126:127], v[184:185]
	v_pk_mul_f32 v[182:183], v[96:97], v[106:107]
	v_add_f32_e32 v167, v184, v185
	ds_read_b128 v[90:93], v84 offset:11840
	ds_read_b128 v[94:97], v84 offset:12096
	ds_read_b128 v[120:123], v84 offset:11168
	ds_read_b128 v[124:127], v84 offset:11424
	ds_read_b128 v[138:141], v86 offset:37968
	s_waitcnt vmcnt(0)
	s_bitcmp1_b32 s28, 0
	s_cselect_b32 s2, 0x4a00, 0
	s_cselect_b32 s5, 0x80, 0
	s_add_i32 s2, s63, s2
	v_lshl_add_u32 v8, v50, 2, s2
	v_add3_u32 v18, v8, v51, v52
	v_lshlrev_b32_e32 v12, 16, v0
	v_and_b32_e32 v13, 0xffff0000, v0
	v_lshlrev_b32_e32 v14, 16, v1
	v_and_b32_e32 v15, 0xffff0000, v1
	ds_write_b128 v18, v[12:15]
	v_lshlrev_b32_e32 v12, 16, v2
	v_and_b32_e32 v13, 0xffff0000, v2
	v_lshlrev_b32_e32 v14, 16, v3
	v_and_b32_e32 v15, 0xffff0000, v3
	ds_write_b128 v18, v[12:15] offset:16
	v_lshl_add_u32 v8, v53, 2, s2
	v_add3_u32 v18, v8, v51, v52
	v_lshlrev_b32_e32 v12, 16, v4
	v_and_b32_e32 v13, 0xffff0000, v4
	v_lshlrev_b32_e32 v14, 16, v5
	v_and_b32_e32 v15, 0xffff0000, v5
	ds_write_b128 v18, v[12:15]
	v_lshlrev_b32_e32 v12, 16, v6
	v_and_b32_e32 v13, 0xffff0000, v6
	v_lshlrev_b32_e32 v14, 16, v7
	v_and_b32_e32 v15, 0xffff0000, v7
	ds_write_b128 v18, v[12:15] offset:16
	v_lshlrev_b32_e32 v9, 16, v49
	v_mul_f32_e32 v10, v54, v9
	v_add_u32_e32 v11, s2, v83
	ds_write2_b32 v11, v10, v10 offset1:1
	s_bitcmp1_b32 s28, 0
	s_cselect_b32 s12, 0x400, 0
	s_add_i32 s12, s63, s12
	v_add_u32_e32 v11, s12, v80
	ds_write_b32 v11, v9 offset:38912
	v_mul_f32_e32 v9, v54, v46
	v_mul_f32_e32 v9, 0xbfb8aa3b, v9
	v_exp_f32_e32 v9, v9
	v_lshl_add_u32 v8, v45, 3, s63
	v_add_u32_e32 v8, s5, v8
	v_add_u32_e32 v8, 0x9400, v8
	ds_write2_b32 v8, v9, v9 offset1:1
	s_cmpk_gt_i32 s4, 0x7e
	s_cbranch_scc1 .Lsd_skipgl
	s_add_i32 s5, s4, 2
	s_lshl_b32 s5, s5, 4
	s_add_i32 s5, s5, s11
	v_add_u32_e32 v8, s5, v45
	v_add_u32_e32 v0, s5, v47
	v_add_u32_e32 v4, s5, v48
	v_ashrrev_i32_e32 v9, 31, v8
	v_mad_i64_i32 v[0:1], s[12:13], v0, s0, v[30:31]
	v_mad_i64_i32 v[4:5], s[12:13], v4, s0, v[30:31]
	v_mad_i64_i32 v[10:11], s[12:13], v8, s0, v[26:27]
	v_lshl_add_u64 v[8:9], v[8:9], 4, s[40:41]
	global_load_dwordx4 v[0:3], v[0:1], off offset:512
	global_load_dwordx4 v[4:7], v[4:5], off offset:512
	global_load_ushort v49, v[10:11], off
	global_load_dword v54, v[8:9], off

; __device__ __forceinline__ void rwkv_scan_unit(CP p, int u, char* smem) {
;     ...
;   for (int c = 0; c < NCH; ++c) {
;     if (c + 1 < NCH) gload(c + 1);
.Lrw_head:
	s_add_i32 s28, s4, 1
	s_cmpk_lg_i32 s4, 100
	s_cbranch_scc1 .Ltw_donerw
	s_cmpk_lt_i32 s57, 112
	s_cbranch_scc1 .Ltw_donerw
	v_readlane_b32 s2, v254, 12
	s_mov_b32 s3, 0
	s_add_i32 s2, s2, 1
	s_lshl_b32 s2, s2, 5

; __device__ __forceinline__ void rwkv_scan_unit(CP p, int u, char* smem) {
;     ...
;     for (int s = 0; s < 16; ++s) {
;       const float* sb = cb + (s + 1) * 384;
;       const float4 om_n = *reinterpret_cast<const float4*>(sb + j * 4);
;       const float4 kk_n = *reinterpret_cast<const float4*>(sb + 64 + j * 4);
;       const float4 bb_n = *reinterpret_cast<const float4*>(sb + 128 + j * 4);
;       const float4 kp_n = *reinterpret_cast<const float4*>(sb + 192 + j * 4);
;       const float4 rr_n = *reinterpret_cast<const float4*>(sb + 256 + j * 4);
;       const float vv_n = sb[320 + rowv];
;       __builtin_amdgcn_sched_barrier(0);
;       float d = s0 * kk.x + s1 * kk.y + s2 * kk.z + s3 * kk.w;
;       d = allreduce16(d);
;       const float sa = -d;
;       s0 = fmaf(-s0, om.x, s0); s1 = fmaf(-s1, om.y, s1); s2 = fmaf(-s2, om.z, s2); s3 = fmaf(-s3, om.w, s3);
;       s0 = fmaf(sa, bb.x, s0); s1 = fmaf(sa, bb.y, s1); s2 = fmaf(sa, bb.z, s2); s3 = fmaf(sa, bb.w, s3);
;       s0 = fmaf(vv, kp.x, s0); s1 = fmaf(vv, kp.y, s1); s2 = fmaf(vv, kp.z, s2); s3 = fmaf(vv, kp.w, s3);
;       float y = s0 * rr.x + s1 * rr.y + s2 * rr.z + s3 * rr.w;
;       y = allreduce16(y);
;       if (j == s) ykeep = y;
;       om = om_n; kk = kk_n; bb = bb_n; kp = kp_n; rr = rr_n; vv = vv_n;
;     }
.Ltw_donerw:
	s_bitcmp1_b32 s4, 0
	s_cselect_b32 s12, 0x6000, 0
	s_add_i32 s13, s63, s12
	v_lshl_add_u32 v78, v77, 2, s13
	v_lshl_add_u32 v79, v48, 2, s13
	ds_read_b128 v[94:97], v78 offset:256
	ds_read_b128 v[90:93], v78 offset:0
	ds_read_b128 v[102:105], v78 offset:768
	ds_read_b32 v110, v79 offset:1280
	ds_read_b128 v[98:101], v78 offset:512
	ds_read_b128 v[106:109], v78 offset:1024
	ds_read_b128 v[116:119], v78 offset:1792
	ds_read_b128 v[112:115], v78 offset:1536
	ds_read_b128 v[124:127], v78 offset:2304
	ds_read_b32 v132, v79 offset:2816
	ds_read_b128 v[120:123], v78 offset:2048
	ds_read_b128 v[128:131], v78 offset:2560
	s_waitcnt lgkmcnt(7)
	v_pk_mul_f32 v[176:177], v[60:61], v[94:95]
	v_pk_fma_f32 v[176:177], v[58:59], v[96:97], v[176:177]
	ds_read_b128 v[138:141], v78 offset:3328
	ds_read_b128 v[134:137], v78 offset:3072
	v_pk_fma_f32 v[180:181], v[60:61], v[90:91], v[60:61] neg_lo:[1,0,0] neg_hi:[1,0,0]
	v_add_f32_e32 v178, v176, v177
	v_pk_fma_f32 v[182:183], v[58:59], v[92:93], v[58:59] neg_lo:[1,0,0] neg_hi:[1,0,0]
	ds_read_b128 v[152:155], v78 offset:3840
	v_add_f32_dpp v178, v178, v178 quad_perm:[1,0,3,2] row_mask:0xf bank_mask:0xf bound_ctrl:1
	v_pk_fma_f32 v[180:181], v[110:111], v[102:103], v[180:181] op_sel_hi:[0,1,1]
	v_pk_fma_f32 v[182:183], v[110:111], v[104:105], v[182:183] op_sel_hi:[0,1,1]
	v_add_f32_dpp v178, v178, v178 quad_perm:[2,3,0,1] row_mask:0xf bank_mask:0xf bound_ctrl:1
	ds_read_b32 v146, v79 offset:4352
	ds_read_b128 v[142:145], v78 offset:3584
	v_add_f32_dpp v178, v178, v178 row_half_mirror row_mask:0xf bank_mask:0xf bound_ctrl:1
	ds_read_b128 v[156:159], v78 offset:4096
	s_nop 0
	v_add_f32_dpp v178, v178, v178 row_mirror row_mask:0xf bank_mask:0xf bound_ctrl:1
	v_pk_fma_f32 v[60:61], v[178:179], v[98:99], v[180:181] op_sel_hi:[0,1,1] neg_lo:[1,0,0] neg_hi:[1,0,0]
	v_pk_fma_f32 v[58:59], v[178:179], v[100:101], v[182:183] op_sel_hi:[0,1,1] neg_lo:[1,0,0] neg_hi:[1,0,0]
	s_waitcnt lgkmcnt(7)
	v_pk_mul_f32 v[176:177], v[60:61], v[116:117]
	v_pk_fma_f32 v[176:177], v[58:59], v[118:119], v[176:177]
	ds_read_b128 v[94:97], v78 offset:4864
	ds_read_b128 v[90:93], v78 offset:4608
	v_pk_fma_f32 v[180:181], v[60:61], v[112:113], v[60:61] neg_lo:[1,0,0] neg_hi:[1,0,0]
	v_add_f32_e32 v178, v176, v177
	v_pk_fma_f32 v[182:183], v[58:59], v[114:115], v[58:59] neg_lo:[1,0,0] neg_hi:[1,0,0]
	ds_read_b128 v[102:105], v78 offset:5376
	v_add_f32_dpp v178, v178, v178 quad_perm:[1,0,3,2] row_mask:0xf bank_mask:0xf bound_ctrl:1
	v_pk_fma_f32 v[180:181], v[132:133], v[124:125], v[180:181] op_sel_hi:[0,1,1]
	v_pk_fma_f32 v[182:183], v[132:133], v[126:127], v[182:183] op_sel_hi:[0,1,1]
	v_add_f32_dpp v178, v178, v178 quad_perm:[2,3,0,1] row_mask:0xf bank_mask:0xf bound_ctrl:1
	v_pk_mul_f32 v[184:185], v[60:61], v[106:107]
	v_pk_fma_f32 v[184:185], v[58:59], v[108:109], v[184:185]
	v_add_f32_dpp v178, v178, v178 row_half_mirror row_mask:0xf bank_mask:0xf bound_ctrl:1
	v_add_f32_e32 v160, v184, v185
	ds_read_b32 v110, v79 offset:5888
	v_add_f32_dpp v178, v178, v178 row_mirror row_mask:0xf bank_mask:0xf bound_ctrl:1
	ds_read_b128 v[98:101], v78 offset:5120
	ds_read_b128 v[106:109], v78 offset:5632
	v_pk_fma_f32 v[60:61], v[178:179], v[120:121], v[180:181] op_sel_hi:[0,1,1] neg_lo:[1,0,0] neg_hi:[1,0,0]
	v_pk_fma_f32 v[58:59], v[178:179], v[122:123], v[182:183] op_sel_hi:[0,1,1] neg_lo:[1,0,0] neg_hi:[1,0,0]
	s_waitcnt lgkmcnt(7)
	v_pk_mul_f32 v[176:177], v[60:61], v[138:139]
	v_pk_fma_f32 v[176:177], v[58:59], v[140:141], v[176:177]
	ds_read_b128 v[116:119], v78 offset:6400
	ds_read_b128 v[112:115], v78 offset:6144
	v_pk_fma_f32 v[180:181], v[60:61], v[134:135], v[60:61] neg_lo:[1,0,0] neg_hi:[1,0,0]
	v_add_f32_e32 v178, v176, v177
	v_pk_fma_f32 v[182:183], v[58:59], v[136:137], v[58:59] neg_lo:[1,0,0] neg_hi:[1,0,0]
	ds_read_b128 v[124:127], v78 offset:6912
	v_add_f32_dpp v178, v178, v178 quad_perm:[1,0,3,2] row_mask:0xf bank_mask:0xf bound_ctrl:1
	v_pk_fma_f32 v[180:181], v[146:147], v[152:153], v[180:181] op_sel_hi:[0,1,1]
	v_pk_fma_f32 v[182:183], v[146:147], v[154:155], v[182:183] op_sel_hi:[0,1,1]
	v_add_f32_dpp v178, v178, v178 quad_perm:[2,3,0,1] row_mask:0xf bank_mask:0xf bound_ctrl:1
	v_pk_mul_f32 v[184:185], v[60:61], v[128:129]
	v_pk_fma_f32 v[184:185], v[58:59], v[130:131], v[184:185]
	v_add_f32_dpp v178, v178, v178 row_half_mirror row_mask:0xf bank_mask:0xf bound_ctrl:1
	v_add_f32_e32 v161, v184, v185
	ds_read_b32 v132, v79 offset:7424
	v_add_f32_dpp v178, v178, v178 row_mirror row_mask:0xf bank_mask:0xf bound_ctrl:1
	ds_read_b128 v[120:123], v78 offset:6656
	ds_read_b128 v[128:131], v78 offset:7168
	v_pk_fma_f32 v[60:61], v[178:179], v[142:143], v[180:181] op_sel_hi:[0,1,1] neg_lo:[1,0,0] neg_hi:[1,0,0]
	v_pk_fma_f32 v[58:59], v[178:179], v[144:145], v[182:183] op_sel_hi:[0,1,1] neg_lo:[1,0,0] neg_hi:[1,0,0]
	s_waitcnt lgkmcnt(7)
	v_pk_mul_f32 v[176:177], v[60:61], v[94:95]
	v_pk_fma_f32 v[176:177], v[58:59], v[96:97], v[176:177]
	ds_read_b128 v[138:141], v78 offset:7936
	ds_read_b128 v[134:137], v78 offset:7680
	v_pk_fma_f32 v[180:181], v[60:61], v[90:91], v[60:61] neg_lo:[1,0,0] neg_hi:[1,0,0]
	v_add_f32_e32 v178, v176, v177
	v_pk_fma_f32 v[182:183], v[58:59], v[92:93], v[58:59] neg_lo:[1,0,0] neg_hi:[1,0,0]
	ds_read_b128 v[152:155], v78 offset:8448
	v_add_f32_dpp v178, v178, v178 quad_perm:[1,0,3,2] row_mask:0xf bank_mask:0xf bound_ctrl:1
	v_pk_fma_f32 v[180:181], v[110:111], v[102:103], v[180:181] op_sel_hi:[0,1,1]
	v_pk_fma_f32 v[182:183], v[110:111], v[104:105], v[182:183] op_sel_hi:[0,1,1]
	v_add_f32_dpp v178, v178, v178 quad_perm:[2,3,0,1] row_mask:0xf bank_mask:0xf bound_ctrl:1
	v_pk_mul_f32 v[184:185], v[60:61], v[156:157]
	v_pk_fma_f32 v[184:185], v[58:59], v[158:159], v[184:185]
	v_add_f32_dpp v178, v178, v178 row_half_mirror row_mask:0xf bank_mask:0xf bound_ctrl:1
	v_add_f32_e32 v162, v184, v185
	ds_read_b32 v146, v79 offset:8960
	v_add_f32_dpp v178, v178, v178 row_mirror row_mask:0xf bank_mask:0xf bound_ctrl:1
	ds_read_b128 v[142:145], v78 offset:8192
	ds_read_b128 v[156:159], v78 offset:8704
	v_pk_fma_f32 v[60:61], v[178:179], v[98:99], v[180:181] op_sel_hi:[0,1,1] neg_lo:[1,0,0] neg_hi:[1,0,0]
	v_pk_fma_f32 v[58:59], v[178:179], v[100:101], v[182:183] op_sel_hi:[0,1,1] neg_lo:[1,0,0] neg_hi:[1,0,0]
	s_waitcnt lgkmcnt(7)
; __device__ __forceinline__ void rwkv_scan_unit(CP p, int u, char* smem) {
;     ...
;     for (int s = 0; s < 16; ++s) {
;       const float* sb = cb + (s + 1) * 384;
;       const float4 om_n = *reinterpret_cast<const float4*>(sb + j * 4);
;       const float4 kk_n = *reinterpret_cast<const float4*>(sb + 64 + j * 4);
;       const float4 bb_n = *reinterpret_cast<const float4*>(sb + 128 + j * 4);
;       const float4 kp_n = *reinterpret_cast<const float4*>(sb + 192 + j * 4);
;       const float4 rr_n = *reinterpret_cast<const float4*>(sb + 256 + j * 4);
;       const float vv_n = sb[320 + rowv];
;       __builtin_amdgcn_sched_barrier(0);
;       float d = s0 * kk.x + s1 * kk.y + s2 * kk.z + s3 * kk.w;
;       d = allreduce16(d);
;       const float sa = -d;
;       s0 = fmaf(-s0, om.x, s0); s1 = fmaf(-s1, om.y, s1); s2 = fmaf(-s2, om.z, s2); s3 = fmaf(-s3, om.w, s3);
;       s0 = fmaf(sa, bb.x, s0); s1 = fmaf(sa, bb.y, s1); s2 = fmaf(sa, bb.z, s2); s3 = fmaf(sa, bb.w, s3);
;       s0 = fmaf(vv, kp.x, s0); s1 = fmaf(vv, kp.y, s1); s2 = fmaf(vv, kp.z, s2); s3 = fmaf(vv, kp.w, s3);
;       float y = s0 * rr.x + s1 * rr.y + s2 * rr.z + s3 * rr.w;
;       y = allreduce16(y);
;       if (j == s) ykeep = y;
;       om = om_n; kk = kk_n; bb = bb_n; kp = kp_n; rr = rr_n; vv = vv_n;
;     }
	v_pk_mul_f32 v[176:177], v[60:61], v[116:117]
	v_pk_fma_f32 v[176:177], v[58:59], v[118:119], v[176:177]
	ds_read_b128 v[94:97], v78 offset:9472
	ds_read_b128 v[90:93], v78 offset:9216
	v_pk_fma_f32 v[180:181], v[60:61], v[112:113], v[60:61] neg_lo:[1,0,0] neg_hi:[1,0,0]
	v_add_f32_e32 v178, v176, v177
	v_pk_fma_f32 v[182:183], v[58:59], v[114:115], v[58:59] neg_lo:[1,0,0] neg_hi:[1,0,0]
	ds_read_b128 v[102:105], v78 offset:9984
	v_add_f32_dpp v178, v178, v178 quad_perm:[1,0,3,2] row_mask:0xf bank_mask:0xf bound_ctrl:1
	v_pk_fma_f32 v[180:181], v[132:133], v[124:125], v[180:181] op_sel_hi:[0,1,1]
	v_pk_fma_f32 v[182:183], v[132:133], v[126:127], v[182:183] op_sel_hi:[0,1,1]
	v_add_f32_dpp v178, v178, v178 quad_perm:[2,3,0,1] row_mask:0xf bank_mask:0xf bound_ctrl:1
	v_pk_mul_f32 v[184:185], v[60:61], v[106:107]
	v_pk_fma_f32 v[184:185], v[58:59], v[108:109], v[184:185]
	v_add_f32_dpp v178, v178, v178 row_half_mirror row_mask:0xf bank_mask:0xf bound_ctrl:1
	v_add_f32_e32 v163, v184, v185
	ds_read_b32 v110, v79 offset:10496
	v_add_f32_dpp v178, v178, v178 row_mirror row_mask:0xf bank_mask:0xf bound_ctrl:1
	ds_read_b128 v[98:101], v78 offset:9728
	ds_read_b128 v[106:109], v78 offset:10240
	v_pk_fma_f32 v[60:61], v[178:179], v[120:121], v[180:181] op_sel_hi:[0,1,1] neg_lo:[1,0,0] neg_hi:[1,0,0]
	v_pk_fma_f32 v[58:59], v[178:179], v[122:123], v[182:183] op_sel_hi:[0,1,1] neg_lo:[1,0,0] neg_hi:[1,0,0]
	s_waitcnt lgkmcnt(7)
	v_pk_mul_f32 v[176:177], v[60:61], v[138:139]
	v_pk_fma_f32 v[176:177], v[58:59], v[140:141], v[176:177]
	ds_read_b128 v[116:119], v78 offset:11008
	ds_read_b128 v[112:115], v78 offset:10752
	v_pk_fma_f32 v[180:181], v[60:61], v[134:135], v[60:61] neg_lo:[1,0,0] neg_hi:[1,0,0]
	v_add_f32_e32 v178, v176, v177
	v_pk_fma_f32 v[182:183], v[58:59], v[136:137], v[58:59] neg_lo:[1,0,0] neg_hi:[1,0,0]
	ds_read_b128 v[124:127], v78 offset:11520
	v_add_f32_dpp v178, v178, v178 quad_perm:[1,0,3,2] row_mask:0xf bank_mask:0xf bound_ctrl:1
	v_pk_fma_f32 v[180:181], v[146:147], v[152:153], v[180:181] op_sel_hi:[0,1,1]
	v_pk_fma_f32 v[182:183], v[146:147], v[154:155], v[182:183] op_sel_hi:[0,1,1]
	v_add_f32_dpp v178, v178, v178 quad_perm:[2,3,0,1] row_mask:0xf bank_mask:0xf bound_ctrl:1
	v_pk_mul_f32 v[184:185], v[60:61], v[128:129]
	v_pk_fma_f32 v[184:185], v[58:59], v[130:131], v[184:185]
	v_add_f32_dpp v178, v178, v178 row_half_mirror row_mask:0xf bank_mask:0xf bound_ctrl:1
	v_add_f32_e32 v164, v184, v185
	ds_read_b32 v132, v79 offset:12032
	v_add_f32_dpp v178, v178, v178 row_mirror row_mask:0xf bank_mask:0xf bound_ctrl:1
	ds_read_b128 v[120:123], v78 offset:11264
	ds_read_b128 v[128:131], v78 offset:11776
	v_pk_fma_f32 v[60:61], v[178:179], v[142:143], v[180:181] op_sel_hi:[0,1,1] neg_lo:[1,0,0] neg_hi:[1,0,0]
	v_pk_fma_f32 v[58:59], v[178:179], v[144:145], v[182:183] op_sel_hi:[0,1,1] neg_lo:[1,0,0] neg_hi:[1,0,0]
	s_waitcnt lgkmcnt(7)
	v_pk_mul_f32 v[176:177], v[60:61], v[94:95]
	v_pk_fma_f32 v[176:177], v[58:59], v[96:97], v[176:177]
	ds_read_b128 v[138:141], v78 offset:12544
	ds_read_b128 v[134:137], v78 offset:12288
	v_pk_fma_f32 v[180:181], v[60:61], v[90:91], v[60:61] neg_lo:[1,0,0] neg_hi:[1,0,0]
	v_add_f32_e32 v178, v176, v177
	v_pk_fma_f32 v[182:183], v[58:59], v[92:93], v[58:59] neg_lo:[1,0,0] neg_hi:[1,0,0]
	ds_read_b128 v[152:155], v78 offset:13056
	v_add_f32_dpp v178, v178, v178 quad_perm:[1,0,3,2] row_mask:0xf bank_mask:0xf bound_ctrl:1
	v_pk_fma_f32 v[180:181], v[110:111], v[102:103], v[180:181] op_sel_hi:[0,1,1]
	v_pk_fma_f32 v[182:183], v[110:111], v[104:105], v[182:183] op_sel_hi:[0,1,1]
	v_add_f32_dpp v178, v178, v178 quad_perm:[2,3,0,1] row_mask:0xf bank_mask:0xf bound_ctrl:1
	v_pk_mul_f32 v[184:185], v[60:61], v[156:157]
	v_pk_fma_f32 v[184:185], v[58:59], v[158:159], v[184:185]
	v_add_f32_dpp v178, v178, v178 row_half_mirror row_mask:0xf bank_mask:0xf bound_ctrl:1
	v_add_f32_e32 v165, v184, v185
	ds_read_b32 v146, v79 offset:13568
	v_add_f32_dpp v178, v178, v178 row_mirror row_mask:0xf bank_mask:0xf bound_ctrl:1
	ds_read_b128 v[142:145], v78 offset:12800
	ds_read_b128 v[156:159], v78 offset:13312
	v_pk_fma_f32 v[60:61], v[178:179], v[98:99], v[180:181] op_sel_hi:[0,1,1] neg_lo:[1,0,0] neg_hi:[1,0,0]
	v_pk_fma_f32 v[58:59], v[178:179], v[100:101], v[182:183] op_sel_hi:[0,1,1] neg_lo:[1,0,0] neg_hi:[1,0,0]
	s_waitcnt lgkmcnt(7)
; __device__ __forceinline__ bf16_t f2bf(float f) { return (bf16_t)(pack2(f, 0.f) & 0xffffu); }
; __device__ __forceinline__ void rwkv_scan_unit(CP p, int u, char* smem) {
;     ...
;   auto gload = [&](int c) {
;     const int rb = rowof(b, c * 16);
; #pragma unroll
;     for (int x = 0; x < 3; ++x) {
;       const int e = tid + x * 256, tok = e / 48, rem = e % 48, vec = rem >> 3, part = rem & 7;
;       st[x] = *reinterpret_cast<const uint4*>(RW + (size_t)(rb + tok) * 1536 + vec * 256 + h * 64 + part * 8);
;     }
;   };
;   auto lwrite = [&](int bi) {
; #pragma unroll
;     for (int x = 0; x < 3; ++x) {
;       const int e = tid + x * 256, tok = e / 48, rem = e % 48, vec = rem >> 3, part = rem & 7;
;       float* d = buf + bi * 6144 + tok * 384 + vec * 64 + part * 8;
;       *reinterpret_cast<float4*>(d) = make_float4(lo2f(st[x].x), hi2f(st[x].x), lo2f(st[x].y), hi2f(st[x].y));
;       *reinterpret_cast<float4*>(d + 4) = make_float4(lo2f(st[x].z), hi2f(st[x].z), lo2f(st[x].w), hi2f(st[x].w));
;     }
;   };
;     ...
;     for (int s = 0; s < 16; ++s) {
;       const float* sb = cb + (s + 1) * 384;
;       const float4 om_n = *reinterpret_cast<const float4*>(sb + j * 4);
;       const float4 kk_n = *reinterpret_cast<const float4*>(sb + 64 + j * 4);
;       const float4 bb_n = *reinterpret_cast<const float4*>(sb + 128 + j * 4);
;       const float4 kp_n = *reinterpret_cast<const float4*>(sb + 192 + j * 4);
;       const float4 rr_n = *reinterpret_cast<const float4*>(sb + 256 + j * 4);
;       const float vv_n = sb[320 + rowv];
;       __builtin_amdgcn_sched_barrier(0);
;       float d = s0 * kk.x + s1 * kk.y + s2 * kk.z + s3 * kk.w;
;       d = allreduce16(d);
;       const float sa = -d;
;       s0 = fmaf(-s0, om.x, s0); s1 = fmaf(-s1, om.y, s1); s2 = fmaf(-s2, om.z, s2); s3 = fmaf(-s3, om.w, s3);
;       s0 = fmaf(sa, bb.x, s0); s1 = fmaf(sa, bb.y, s1); s2 = fmaf(sa, bb.z, s2); s3 = fmaf(sa, bb.w, s3);
;       s0 = fmaf(vv, kp.x, s0); s1 = fmaf(vv, kp.y, s1); s2 = fmaf(vv, kp.z, s2); s3 = fmaf(vv, kp.w, s3);
;       float y = s0 * rr.x + s1 * rr.y + s2 * rr.z + s3 * rr.w;
;       y = allreduce16(y);
;       if (j == s) ykeep = y;
;       om = om_n; kk = kk_n; bb = bb_n; kp = kp_n; rr = rr_n; vv = vv_n;
;     }
;     Y[(size_t)(rowof(b, c * 16) + j) * 1024 + 256 + h * 64 + rowv] = f2bf(ykeep);
;     if (c + 1 < NCH) lwrite((c + 1) & 1);
	v_pk_mul_f32 v[176:177], v[60:61], v[116:117]
	v_pk_fma_f32 v[176:177], v[58:59], v[118:119], v[176:177]
	ds_read_b128 v[94:97], v78 offset:14080
	ds_read_b128 v[90:93], v78 offset:13824
	v_pk_fma_f32 v[180:181], v[60:61], v[112:113], v[60:61] neg_lo:[1,0,0] neg_hi:[1,0,0]
	v_add_f32_e32 v178, v176, v177
	v_pk_fma_f32 v[182:183], v[58:59], v[114:115], v[58:59] neg_lo:[1,0,0] neg_hi:[1,0,0]
	ds_read_b128 v[102:105], v78 offset:14592
	v_add_f32_dpp v178, v178, v178 quad_perm:[1,0,3,2] row_mask:0xf bank_mask:0xf bound_ctrl:1
	v_pk_fma_f32 v[180:181], v[132:133], v[124:125], v[180:181] op_sel_hi:[0,1,1]
	v_pk_fma_f32 v[182:183], v[132:133], v[126:127], v[182:183] op_sel_hi:[0,1,1]
	v_add_f32_dpp v178, v178, v178 quad_perm:[2,3,0,1] row_mask:0xf bank_mask:0xf bound_ctrl:1
	v_pk_mul_f32 v[184:185], v[60:61], v[106:107]
	v_pk_fma_f32 v[184:185], v[58:59], v[108:109], v[184:185]
	v_add_f32_dpp v178, v178, v178 row_half_mirror row_mask:0xf bank_mask:0xf bound_ctrl:1
	v_add_f32_e32 v166, v184, v185
	ds_read_b32 v110, v79 offset:15104
	v_add_f32_dpp v178, v178, v178 row_mirror row_mask:0xf bank_mask:0xf bound_ctrl:1
	ds_read_b128 v[98:101], v78 offset:14336
	ds_read_b128 v[106:109], v78 offset:14848
	v_pk_fma_f32 v[60:61], v[178:179], v[120:121], v[180:181] op_sel_hi:[0,1,1] neg_lo:[1,0,0] neg_hi:[1,0,0]
	v_pk_fma_f32 v[58:59], v[178:179], v[122:123], v[182:183] op_sel_hi:[0,1,1] neg_lo:[1,0,0] neg_hi:[1,0,0]
	s_waitcnt vmcnt(0)
	s_bitcmp1_b32 s28, 0
	s_cselect_b32 s2, 0x6000, 0
	s_add_i32 s2, s63, s2
	v_lshl_add_u32 v12, v67, 2, s2
	v_add3_u32 v18, v12, v68, v69
	v_lshlrev_b32_e32 v12, 16, v0
	v_and_b32_e32 v13, 0xffff0000, v0
	v_lshlrev_b32_e32 v14, 16, v1
	v_and_b32_e32 v15, 0xffff0000, v1
	ds_write_b128 v18, v[12:15]
	v_lshlrev_b32_e32 v12, 16, v2
	v_and_b32_e32 v13, 0xffff0000, v2
	v_lshlrev_b32_e32 v14, 16, v3
	v_and_b32_e32 v15, 0xffff0000, v3
	ds_write_b128 v18, v[12:15] offset:16
	v_lshl_add_u32 v12, v70, 2, s2
	v_add3_u32 v18, v12, v71, v72
	v_lshlrev_b32_e32 v12, 16, v4
	v_and_b32_e32 v13, 0xffff0000, v4
	v_lshlrev_b32_e32 v14, 16, v5
	v_and_b32_e32 v15, 0xffff0000, v5
	ds_write_b128 v18, v[12:15]
	v_lshlrev_b32_e32 v12, 16, v6
	v_and_b32_e32 v13, 0xffff0000, v6
	v_lshlrev_b32_e32 v14, 16, v7
	v_and_b32_e32 v15, 0xffff0000, v7
	ds_write_b128 v18, v[12:15] offset:16
	v_lshl_add_u32 v12, v73, 2, s2
	v_add3_u32 v18, v12, v74, v75
	v_lshlrev_b32_e32 v12, 16, v8
	v_and_b32_e32 v13, 0xffff0000, v8
	v_lshlrev_b32_e32 v14, 16, v9
	v_and_b32_e32 v15, 0xffff0000, v9
	ds_write_b128 v18, v[12:15]
	v_lshlrev_b32_e32 v12, 16, v10
	v_and_b32_e32 v13, 0xffff0000, v10
	v_lshlrev_b32_e32 v14, 16, v11
	v_and_b32_e32 v15, 0xffff0000, v11
	ds_write_b128 v18, v[12:15] offset:16
	s_cmpk_gt_i32 s4, 0x7e
	s_cbranch_scc1 .Lrw_skipgl
	s_add_i32 s5, s4, 2
	s_lshl_b32 s5, s5, 4
	s_add_i32 s5, s5, s11
	v_add_u32_e32 v0, s5, v63
	v_add_u32_e32 v2, s5, v65
	v_add_u32_e32 v8, s5, v66
	v_mad_i64_i32 v[0:1], s[12:13], v0, s66, v[50:51]
	v_mad_i64_i32 v[4:5], s[12:13], v2, s66, v[52:53]
	v_mad_i64_i32 v[8:9], s[12:13], v8, s66, v[54:55]
	global_load_dwordx4 v[0:3], v[0:1], off
	global_load_dwordx4 v[4:7], v[4:5], off
	global_load_dwordx4 v[8:11], v[8:9], off

; __device__ __forceinline__ int tidx() { int t = threadIdx.x & 255; asm volatile("" : "+v"(t)); return t; }
; __device__ __forceinline__ void prep_unit(CP p, int l, int u, char* smem) {
;   float* pm = (float*)smem;
;   bf16_t* latA = (bf16_t*)(smem + 16 * PMS * 4);
;   bf16_t* xcA = latA + 16 * LSTR;
;   const int tid = tidx(), lane = tid & 63, wid = tid >> 6, fr = lane & 15, fq = lane >> 4;
;   const int b = u / 129, t0 = (u % 129) * 16;
;   const int r0 = rowof(b, t0);
;   const bf16_t* proj = (const bf16_t*)(p.ws + WS_PROJ);
;   bf16_t* RW = (bf16_t*)(p.ws + WS_RW);
;   bf16_t* SS = (bf16_t*)(p.ws + WS_SS);
;   bf16_t* LR = (bf16_t*)(p.ws + WS_LR);
;   bf16_t* RG = (bf16_t*)(p.ws + WS_RG);
;   float* RC = (float*)(p.ws + WS_RC);
;   float* SD = (float*)(p.ws + WS_SD);
;   const int rm1 = (t0 > 0) ? rowof(b, t0 - 1) : 0, rm2 = (t0 > 0) ? rowof(b, t0 - 2) : 0, rm3 = (t0 > 0) ? rowof(b, t0 - 3) : 0;
;     ...
;     const float inv = 1.f / fmaxf(sqrtf(ss), 1e-12f);
;     float4 w0a[4], baa[4], bxa[4], lama[4];
; #pragma unroll
;     for (int mf = 0; mf < 4; ++mf) {
;       const int c = wid * 64 + mf * 16 + fq * 4;
;       w0a[mf] = *reinterpret_cast<const float4*>(p.in[15] + l * 256 + c);
;       baa[mf] = *reinterpret_cast<const float4*>(p.in[28] + l * 256 + c);
;       bxa[mf] = *reinterpret_cast<const float4*>(p.in[30] + l * 256 + c);
;       lama[mf] = *reinterpret_cast<const float4*>(p.in[31] + l * 256 + c);
;     }
;     if (fq == 0) RC[row * 4 + wid] = cf;
; #pragma unroll
;     for (int mf = 0; mf < 4; ++mf) {
;       const int c = wid * 64 + mf * 16 + fq * 4;
;       const float4 w0 = w0a[mf], ba = baa[mf], bx = bxa[mf], lam = lama[mf];
.Lprep_entry:
	v_writelane_b32 v254, s79, 18
	v_writelane_b32 v254, s78, 19
	v_writelane_b32 v254, s47, 20
	v_writelane_b32 v254, s7, 21
	s_cmpk_gt_i32 s54, 0x407
	v_readlane_b32 s48, v253, 61
	v_readlane_b32 s49, v253, 62
	s_cbranch_scc1 .LBB0_858
	v_readlane_b32 s0, v254, 12
	s_mul_i32 s10, s0, 0xc00
	s_mul_i32 s2, s0, 0x300
	s_ashr_i32 s11, s10, 31
	s_ashr_i32 s3, s2, 31
	s_add_u32 s44, s92, 0xcb30800
	s_addc_u32 s45, s93, 0
	v_readlane_b32 s1, v254, 13
	s_add_u32 s0, s92, 0xfb90800
	s_addc_u32 s1, s93, 0
	v_writelane_b32 v254, s0, 22
	s_mov_b32 s78, s54
	s_nop 0
	v_writelane_b32 v254, s1, 23
	s_add_u32 s0, s92, 0xfbd1000
	s_addc_u32 s1, s93, 0
	v_writelane_b32 v254, s0, 24
	s_nop 1
	v_writelane_b32 v254, s1, 25
	v_readlane_b32 s0, v253, 63
	v_readlane_b32 s1, v254, 0
	s_load_dwordx4 s[40:43], s[0:1], 0x70
	s_load_dwordx4 s[48:51], s[0:1], 0x40
	v_readlane_b32 s4, v254, 3
	v_readlane_b32 s5, v254, 4
	s_lshl_b64 s[28:29], s[4:5], 2
	s_load_dwordx2 s[4:5], s[0:1], 0x88
	s_load_dwordx4 s[12:15], s[0:1], 0xc8
	s_waitcnt lgkmcnt(0)
	s_add_u32 s8, s40, s28
	s_addc_u32 s9, s41, s29
	v_writelane_b32 v254, s8, 9
	s_lshl_b64 s[10:11], s[10:11], 2
	s_nop 0
	v_writelane_b32 v254, s9, 10
	s_add_u32 s8, s48, s10
	s_addc_u32 s9, s49, s11
	s_add_u32 s12, s12, s28
	s_addc_u32 s13, s13, s29
	s_lshl_b64 s[2:3], s[2:3], 2
	v_writelane_b32 v254, s12, 26
	s_add_u32 s2, s50, s2
	s_addc_u32 s3, s51, s3
	v_writelane_b32 v254, s13, 27
	v_writelane_b32 v254, s2, 28
	s_load_dwordx2 s[10:11], s[0:1], 0xe0
	v_readlane_b32 s48, v253, 61
	v_writelane_b32 v254, s3, 29
	s_lshl_b64 s[2:3], s[74:75], 2
	s_add_u32 s12, s14, s2
	s_addc_u32 s13, s15, s3
	v_writelane_b32 v254, s12, 30
	v_readlane_b32 s49, v253, 62
	s_nop 0
	v_writelane_b32 v254, s13, 31
	s_add_u32 s12, s8, 0xc00
	s_addc_u32 s13, s9, 0
	v_writelane_b32 v254, s12, 32
	s_nop 1
	v_writelane_b32 v254, s13, 33
	s_add_u32 s12, s8, 0x1800
	s_addc_u32 s13, s9, 0
	v_writelane_b32 v254, s12, 34
	s_nop 1
	v_writelane_b32 v254, s13, 35
	s_add_u32 s12, s8, 0x2400
	v_writelane_b32 v254, s8, 14
	s_addc_u32 s13, s9, 0
	s_nop 0
	v_writelane_b32 v254, s9, 15
	v_writelane_b32 v254, s12, 36
	s_add_u32 s8, s92, 0xd8000
	s_addc_u32 s9, s93, 0
	v_writelane_b32 v254, s13, 37
	v_writelane_b32 v254, s8, 38
	s_load_dwordx2 s[28:29], s[0:1], 0xb0
	s_load_dwordx4 s[12:15], s[0:1], 0xa0
	v_writelane_b32 v254, s9, 39
	s_add_u32 s8, s92, 0xf0000
	s_addc_u32 s9, s93, 0
	v_writelane_b32 v254, s8, 40
	s_nop 1
	v_writelane_b32 v254, s9, 41
	s_add_u32 s8, s92, 0xe0000
	s_addc_u32 s9, s93, 0
	v_writelane_b32 v254, s8, 42
	s_nop 1
	v_writelane_b32 v254, s9, 43
	s_add_u32 s8, s92, 0xd0000
	s_addc_u32 s9, s93, 0
	v_writelane_b32 v254, s8, 44
	s_nop 1
	v_writelane_b32 v254, s9, 45
	s_add_u32 s8, s92, 0xf8000
	s_addc_u32 s9, s93, 0
	v_writelane_b32 v254, s8, 46
	s_add_u32 s4, s4, s2
	s_addc_u32 s5, s5, s3
	v_writelane_b32 v254, s9, 47
	v_writelane_b32 v254, s4, 48
	s_nop 1
	v_writelane_b32 v254, s5, 49
	s_waitcnt lgkmcnt(0)
	s_add_u32 s4, s12, s2
	s_addc_u32 s5, s13, s3
	v_writelane_b32 v254, s4, 50
	s_nop 1
	v_writelane_b32 v254, s5, 51
	s_add_u32 s4, s14, s2
	s_addc_u32 s5, s15, s3
	v_writelane_b32 v254, s4, 52
	s_load_dwordx4 s[12:15], s[0:1], 0xf0
	s_nop 0
	v_writelane_b32 v254, s5, 53
	s_add_u32 s4, s28, s2
	s_addc_u32 s5, s29, s3
	v_writelane_b32 v254, s4, 54
	s_add_u32 s0, s42, s2
	s_addc_u32 s1, s43, s3
	v_writelane_b32 v254, s5, 55
	v_writelane_b32 v254, s0, 56
	s_nop 1
	v_writelane_b32 v254, s1, 57
	s_add_u32 s0, s10, s2
	s_addc_u32 s1, s11, s3
	v_writelane_b32 v254, s0, 58
	s_nop 1
	v_writelane_b32 v254, s1, 59
	s_waitcnt lgkmcnt(0)
	s_add_u32 s0, s12, s2
	s_addc_u32 s1, s13, s3
	v_writelane_b32 v254, s0, 60
	s_nop 1
	v_writelane_b32 v254, s1, 61
	s_add_u32 s0, s14, s2
	s_addc_u32 s1, s15, s3
	v_writelane_b32 v254, s0, 62
	s_nop 1
	v_writelane_b32 v254, s1, 63
	s_add_u32 s0, s92, 0xf380800
	s_addc_u32 s1, s93, 0
	v_writelane_b32 v255, s0, 0
	s_nop 1
	v_writelane_b32 v255, s1, 1
	s_add_u32 s0, s92, 0xe360800
	s_addc_u32 s1, s93, 0
	v_writelane_b32 v255, s0, 2
	s_nop 1
	v_writelane_b32 v255, s1, 3
	s_branch .LBB0_655
.LBB0_654:
	s_or_b64 exec, exec, s[2:3]
	s_waitcnt lgkmcnt(1)
	v_add_f32_e32 v146, v148, v203
	s_mov_b32 s4, 0xf800000
	v_cmp_gt_f32_e32 vcc, s4, v146
	v_mul_f32_e32 v148, 0x4f800000, v146
	v_readlane_b32 s0, v254, 1
	v_cndmask_b32_e32 v146, v146, v148, vcc
	v_sqrt_f32_e32 v148, v146
	v_readlane_b32 s1, v254, 2
	s_waitcnt vmcnt(15)
	v_add_f32_e32 v88, v88, v140
	v_max_f32_e64 v140, -v88, 0
	v_add_u32_e32 v202, -1, v148
	v_fma_f32 v203, -v202, v148, v146
	v_cmp_ge_f32_e64 s[38:39], 0, v203
	v_add_u32_e32 v203, 1, v148
	s_waitcnt vmcnt(14)
	v_add_f32_e32 v84, v84, v132
	v_cndmask_b32_e64 v202, v148, v202, s[38:39]
	v_fma_f32 v148, -v203, v148, v146
	v_cmp_lt_f32_e64 s[38:39], 0, v148
	s_waitcnt vmcnt(12)
	v_max_f32_e64 v132, -v128, -v128
	v_add_f32_e32 v80, v80, v136
	v_cndmask_b32_e64 v148, v202, v203, s[38:39]
	v_mul_f32_e32 v202, 0x37800000, v148
	v_cndmask_b32_e32 v148, v148, v202, vcc
	v_cmp_class_f32_e32 vcc, v146, v218
	v_add_f32_e32 v89, v89, v141
	v_add_f32_e32 v85, v85, v133
	v_cndmask_b32_e32 v146, v148, v146, vcc
	v_max_f32_e32 v146, 0x2b8cbccc, v146
	v_div_scale_f32 v148, s[2:3], v146, v146, 1.0
	v_rcp_f32_e32 v202, v148
	v_max_f32_e64 v133, -v129, -v129
	v_mul_f32_e32 v84, 0xbfb8aa3b, v84
	v_mul_f32_e32 v85, 0xbfb8aa3b, v85
	v_fma_f32 v203, -v148, v202, 1.0
	v_fmac_f32_e32 v202, v203, v202
	v_div_scale_f32 v203, vcc, 1.0, v146, 1.0
	v_mul_f32_e32 v204, v203, v202
	s_waitcnt lgkmcnt(0)
; __device__ __forceinline__ float lo2f(unsigned w) { return __uint_as_float(w << 16); }
; __device__ __forceinline__ float hi2f(unsigned w) { return __uint_as_float(w & 0xffff0000u); }
; __device__ __forceinline__ float sigmoidf_(float x) { return __builtin_amdgcn_rcpf(1.f + __expf(-x)); }
; __device__ __forceinline__ float softplus_fast(float x) { return fmaxf(x, 0.f) + __logf(1.f + __expf(-fabsf(x))); }
; __device__ __forceinline__ void prep_unit(CP p, int l, int u, char* smem) {
;     ...
;     const float inv = 1.f / fmaxf(sqrtf(ss), 1e-12f);
;     float4 w0a[4], baa[4], bxa[4], lama[4];
; #pragma unroll
;     for (int mf = 0; mf < 4; ++mf) {
;       const int c = wid * 64 + mf * 16 + fq * 4;
;       w0a[mf] = *reinterpret_cast<const float4*>(p.in[15] + l * 256 + c);
;       baa[mf] = *reinterpret_cast<const float4*>(p.in[28] + l * 256 + c);
;       bxa[mf] = *reinterpret_cast<const float4*>(p.in[30] + l * 256 + c);
;       lama[mf] = *reinterpret_cast<const float4*>(p.in[31] + l * 256 + c);
;     }
;     if (fq == 0) RC[row * 4 + wid] = cf;
; #pragma unroll
;     for (int mf = 0; mf < 4; ++mf) {
;       const int c = wid * 64 + mf * 16 + fq * 4;
;       const float4 w0 = w0a[mf], ba = baa[mf], bx = bxa[mf], lam = lama[mf];
;       const float w0_[4] = {w0.x, w0.y, w0.z, w0.w}, ba_[4] = {ba.x, ba.y, ba.z, ba.w};
;       const float bx_[4] = {bx.x, bx.y, bx.z, bx.w}, lam_[4] = {lam.x, lam.y, lam.z, lam.w};
;       const uint2 xcr = *reinterpret_cast<const uint2*>(xcA + tt * LSTR + c);
;       const float xc_[4] = {lo2f(xcr.x), hi2f(xcr.x), lo2f(xcr.y), hi2f(xcr.y)};
;       float omw[4], kn[4], bb[4], la[4], uu[4];
; #pragma unroll
;       for (int j = 0; j < 4; ++j) {
;         const int x = mf * 4 + j;
;         const float wv = w0_[j] + accw[mf][j];
;         const float w = -softplus_fast(-wv) - 0.5f;
;         omw[j] = 1.f - __expf(-__expf(w));
;         kn[j] = kkv[x] * inv;
;         bb[j] = kn[j] * avv[x];
;         const float rr = sigmoidf_(accr[mf][j] + ba_[j]), ii = sigmoidf_(acci[mf][j] + bx_[j]);
;         la[j] = -8.f * rr * softplus_fast(-lam_[j]);
;         uu[j] = sqrtf(fmaxf(1.f - __expf(2.f * la[j]), 0.f)) * (ii * xc_[j]);
	v_fma_f32 v205, -v148, v204, v203
	v_fmac_f32_e32 v204, v205, v202
	v_fma_f32 v148, -v148, v204, v203
	v_div_fmas_f32 v148, v148, v202, v204
	v_mov_b64_e32 v[202:203], s[0:1]
	v_readlane_b32 s0, v255, 0
	v_mad_i64_i32 v[206:207], s[2:3], v144, s66, v[202:203]
	v_lshlrev_b64 v[202:203], 9, v[144:145]
	v_readlane_b32 s1, v255, 1
	v_lshlrev_b64 v[144:145], 10, v[144:145]
	s_mov_b32 s2, 0x3f317217
	v_lshl_add_u64 v[204:205], s[0:1], 0, v[202:203]
	v_readlane_b32 s0, v255, 2
	v_readlane_b32 s1, v255, 3
	v_exp_f32_e32 v84, v84
	v_exp_f32_e32 v85, v85
	v_lshl_add_u64 v[202:203], s[0:1], 0, v[144:145]
	s_mov_b32 s0, 0xbfb8aa3b
	v_mul_f32_e64 v88, |v88|, s0
	v_exp_f32_e32 v88, v88
	v_mul_f32_e64 v128, |v128|, s0
	v_exp_f32_e32 v128, v128
	s_mov_b32 s1, 0x7f800000
	v_add_f32_e32 v88, 1.0, v88
	v_cmp_gt_f32_e32 vcc, s33, v88
	v_add_f32_e32 v128, 1.0, v128
	v_mul_f32_e64 v129, |v129|, s0
	v_cndmask_b32_e64 v208, 0, 32, vcc
	v_ldexp_f32 v88, v88, v208
	v_log_f32_e32 v88, v88
	v_exp_f32_e32 v129, v129
	v_add_f32_e32 v84, 1.0, v84
	v_add_f32_e32 v85, 1.0, v85
	v_mul_f32_e32 v208, 0x3f317217, v88
	v_fma_f32 v208, v88, s2, -v208
	v_fmac_f32_e32 v208, 0x3377d1cf, v88
	v_fmac_f32_e32 v208, 0x3f317217, v88
	v_cmp_lt_f32_e64 s[38:39], |v88|, s1
	v_add_f32_e32 v129, 1.0, v129
	v_rcp_f32_e32 v84, v84
	v_cndmask_b32_e64 v88, v88, v208, s[38:39]
	v_cndmask_b32_e32 v208, 0, v229, vcc
	v_cmp_gt_f32_e32 vcc, s33, v128
	v_sub_f32_e32 v88, v88, v208
	v_add_f32_e32 v88, v140, v88
	v_cndmask_b32_e64 v136, 0, 32, vcc
	v_ldexp_f32 v128, v128, v136
	v_log_f32_e32 v128, v128
	v_rcp_f32_e32 v85, v85
	v_max_f32_e32 v132, 0, v132
	v_max_f32_e32 v133, 0, v133
	v_mul_f32_e32 v136, 0x3f317217, v128
	v_fma_f32 v136, v128, s2, -v136
	v_fmac_f32_e32 v136, 0x3377d1cf, v128
	v_fmac_f32_e32 v136, 0x3f317217, v128
	v_cmp_lt_f32_e64 s[38:39], |v128|, s1
	s_mov_b32 s6, 0xc1000000
	v_pk_mul_f32 v[84:85], v[84:85], s[6:7] op_sel_hi:[1,0]
	v_cndmask_b32_e64 v128, v128, v136, s[38:39]
	v_cndmask_b32_e32 v136, 0, v229, vcc
	v_sub_f32_e32 v128, v128, v136
	v_max_f32_e64 v136, -v89, 0
	v_mul_f32_e64 v89, |v89|, s0
	v_exp_f32_e32 v89, v89
	v_add_f32_e32 v81, v81, v137
	v_mul_f32_e32 v80, 0xbfb8aa3b, v80
	v_mul_f32_e32 v81, 0xbfb8aa3b, v81
	v_add_f32_e32 v89, 1.0, v89
	v_cmp_gt_f32_e32 vcc, s33, v89
	v_exp_f32_e32 v80, v80
	v_exp_f32_e32 v81, v81
	v_cndmask_b32_e64 v140, 0, 32, vcc
	v_ldexp_f32 v89, v89, v140
	v_log_f32_e32 v89, v89
	v_lshl_add_u32 v144, v186, 1, v147
	v_add_u32_e32 v232, 0xa000, v144
	v_div_fixup_f32 v148, v148, v146, 1.0
	v_mul_f32_e32 v140, 0x3f317217, v89
	v_fma_f32 v140, v89, s2, -v140
	v_fmac_f32_e32 v140, 0x3377d1cf, v89
	v_fmac_f32_e32 v140, 0x3f317217, v89
	v_cmp_lt_f32_e64 s[38:39], |v89|, s1
	ds_read2_b64 v[144:147], v232 offset0:64 offset1:68
	v_add_f32_e32 v80, 1.0, v80
	v_cndmask_b32_e64 v89, v89, v140, s[38:39]
	v_cndmask_b32_e32 v140, 0, v229, vcc
	v_sub_f32_e32 v89, v89, v140
	v_cmp_gt_f32_e32 vcc, s33, v129
	v_add_f32_e32 v89, v136, v89
	v_add_f32_e32 v81, 1.0, v81
	v_cndmask_b32_e64 v136, 0, 32, vcc
	v_ldexp_f32 v129, v129, v136
	v_log_f32_e32 v129, v129
	v_rcp_f32_e32 v80, v80
	v_rcp_f32_e32 v81, v81
	s_waitcnt lgkmcnt(0)
	v_lshlrev_b32_e32 v210, 16, v144
	v_mul_f32_e32 v136, 0x3f317217, v129
	v_fma_f32 v136, v129, s2, -v136
	v_fmac_f32_e32 v136, 0x3377d1cf, v129
	v_fmac_f32_e32 v136, 0x3f317217, v129
	v_cmp_lt_f32_e64 s[38:39], |v129|, s1
	v_and_b32_e32 v211, 0xffff0000, v144
	v_pk_mul_f32 v[80:81], v[80:81], v[210:211]
	v_cndmask_b32_e64 v129, v129, v136, s[38:39]
	v_cndmask_b32_e32 v136, 0, v229, vcc
	v_sub_f32_e32 v129, v129, v136
	v_pk_add_f32 v[128:129], v[132:133], v[128:129]
	v_sub_f32_e32 v88, -0.5, v88
	v_pk_mul_f32 v[84:85], v[84:85], v[128:129]
	v_sub_f32_e32 v89, -0.5, v89
	v_add_f32_e32 v128, v84, v84
	v_mul_f32_e32 v128, 0x3fb8aa3b, v128
	v_exp_f32_e32 v128, v128
	v_mul_f32_e32 v88, 0x3fb8aa3b, v88
	v_mul_f32_e32 v89, 0x3fb8aa3b, v89
	v_exp_f32_e32 v88, v88
	v_sub_f32_e32 v128, 1.0, v128
	v_max_f32_e32 v128, 0, v128
	v_cmp_gt_f32_e32 vcc, s4, v128
	v_mul_f32_e32 v129, 0x4f800000, v128
	v_exp_f32_e32 v89, v89
	v_cndmask_b32_e32 v128, v128, v129, vcc
	v_sqrt_f32_e32 v129, v128
	v_mul_f32_e32 v88, 0xbfb8aa3b, v88
	v_mul_f32_e32 v89, 0xbfb8aa3b, v89
	v_exp_f32_e32 v88, v88
	v_add_u32_e32 v132, -1, v129
	v_fma_f32 v133, -v132, v129, v128
	v_cmp_ge_f32_e64 s[38:39], 0, v133
	v_add_u32_e32 v133, 1, v129
	v_exp_f32_e32 v89, v89
	v_cndmask_b32_e64 v132, v129, v132, s[38:39]
	v_fma_f32 v129, -v133, v129, v128
	v_cmp_lt_f32_e64 s[38:39], 0, v129
	v_lshlrev_b32_e32 v144, 16, v145
	v_and_b32_e32 v145, 0xffff0000, v145
	v_cndmask_b32_e64 v129, v132, v133, s[38:39]
	v_mul_f32_e32 v132, 0x37800000, v129
	v_cndmask_b32_e32 v129, v129, v132, vcc
	v_cmp_class_f32_e32 vcc, v128, v218
	v_pk_mul_f32 v[140:141], v[200:201], v[148:149] op_sel_hi:[1,0]
	v_pk_add_f32 v[208:209], v[88:89], 1.0 op_sel_hi:[1,0] neg_lo:[1,0] neg_hi:[1,0]
	v_cndmask_b32_e32 v128, v129, v128, vcc
	v_add_f32_e32 v129, v85, v85
	v_mul_f32_e32 v129, 0x3fb8aa3b, v129
	v_exp_f32_e32 v129, v129
	v_pk_mul_f32 v[88:89], v[198:199], v[140:141]
	v_cvt_pk_bf16_f32 v76, v76, v77
	v_cvt_pk_bf16_f32 v88, v88, v89
	v_sub_f32_e32 v129, 1.0, v129
	v_max_f32_e32 v129, 0, v129
	v_cmp_gt_f32_e32 vcc, s4, v129
	v_mul_f32_e32 v132, 0x4f800000, v129
	v_cvt_pk_bf16_f32 v77, v78, v79
	v_cndmask_b32_e32 v129, v129, v132, vcc
	v_sqrt_f32_e32 v132, v129
	v_cvt_pk_bf16_f32 v84, v84, v85
	s_waitcnt vmcnt(11)
	v_add_f32_e32 v68, v68, v124
	v_add_f32_e32 v69, v69, v125
	v_add_u32_e32 v133, -1, v132
	v_fma_f32 v136, -v133, v132, v129
	v_cmp_ge_f32_e64 s[38:39], 0, v136
	v_add_u32_e32 v136, 1, v132
	s_waitcnt vmcnt(10)
; __device__ __forceinline__ float lo2f(unsigned w) { return __uint_as_float(w << 16); }
; __device__ __forceinline__ float hi2f(unsigned w) { return __uint_as_float(w & 0xffff0000u); }
; __device__ __forceinline__ float sigmoidf_(float x) { return __builtin_amdgcn_rcpf(1.f + __expf(-x)); }
; __device__ __forceinline__ float softplus_fast(float x) { return fmaxf(x, 0.f) + __logf(1.f + __expf(-fabsf(x))); }
; __device__ __forceinline__ void prep_unit(CP p, int l, int u, char* smem) {
;     ...
;     for (int mf = 0; mf < 4; ++mf) {
;       const int c = wid * 64 + mf * 16 + fq * 4;
;       const float4 w0 = w0a[mf], ba = baa[mf], bx = bxa[mf], lam = lama[mf];
;       const float w0_[4] = {w0.x, w0.y, w0.z, w0.w}, ba_[4] = {ba.x, ba.y, ba.z, ba.w};
;       const float bx_[4] = {bx.x, bx.y, bx.z, bx.w}, lam_[4] = {lam.x, lam.y, lam.z, lam.w};
;       const uint2 xcr = *reinterpret_cast<const uint2*>(xcA + tt * LSTR + c);
;       const float xc_[4] = {lo2f(xcr.x), hi2f(xcr.x), lo2f(xcr.y), hi2f(xcr.y)};
;       float omw[4], kn[4], bb[4], la[4], uu[4];
; #pragma unroll
;       for (int j = 0; j < 4; ++j) {
;         const int x = mf * 4 + j;
;         const float wv = w0_[j] + accw[mf][j];
;         const float w = -softplus_fast(-wv) - 0.5f;
;         omw[j] = 1.f - __expf(-__expf(w));
;         kn[j] = kkv[x] * inv;
;         bb[j] = kn[j] * avv[x];
;         const float rr = sigmoidf_(accr[mf][j] + ba_[j]), ii = sigmoidf_(acci[mf][j] + bx_[j]);
;         la[j] = -8.f * rr * softplus_fast(-lam_[j]);
;         uu[j] = sqrtf(fmaxf(1.f - __expf(2.f * la[j]), 0.f)) * (ii * xc_[j]);
	v_add_f32_e32 v64, v64, v120
	v_cndmask_b32_e64 v133, v132, v133, s[38:39]
	v_fma_f32 v132, -v136, v132, v129
	v_cmp_lt_f32_e64 s[38:39], 0, v132
	v_add_f32_e32 v65, v65, v121
	v_mul_f32_e32 v64, 0xbfb8aa3b, v64
	v_cndmask_b32_e64 v132, v133, v136, s[38:39]
	v_mul_f32_e32 v133, 0x37800000, v132
	v_cndmask_b32_e32 v132, v132, v133, vcc
	v_cmp_class_f32_e32 vcc, v129, v218
	v_mul_f32_e32 v65, 0xbfb8aa3b, v65
	v_exp_f32_e32 v64, v64
	v_cndmask_b32_e32 v129, v132, v129, vcc
	v_pk_mul_f32 v[128:129], v[128:129], v[80:81]
	v_add_f32_e32 v80, v90, v142
	v_max_f32_e64 v81, -v80, 0
	v_mul_f32_e64 v80, |v80|, s0
	v_exp_f32_e32 v80, v80
	s_waitcnt vmcnt(9)
	v_add_f32_e32 v60, v60, v116
	v_exp_f32_e32 v65, v65
	v_add_f32_e32 v61, v61, v117
	v_add_f32_e32 v80, 1.0, v80
	v_cmp_gt_f32_e32 vcc, s33, v80
	v_mul_f32_e32 v60, 0xbfb8aa3b, v60
	v_mul_f32_e32 v61, 0xbfb8aa3b, v61
	v_cndmask_b32_e64 v90, 0, 32, vcc
	v_ldexp_f32 v80, v80, v90
	v_log_f32_e32 v80, v80
	v_exp_f32_e32 v60, v60
	v_exp_f32_e32 v61, v61
	v_add_f32_e32 v64, 1.0, v64
	v_mul_f32_e32 v90, 0x3f317217, v80
	v_fma_f32 v90, v80, s2, -v90
	v_fmac_f32_e32 v90, 0x3377d1cf, v80
	v_fmac_f32_e32 v90, 0x3f317217, v80
	v_cmp_lt_f32_e64 s[38:39], |v80|, s1
	v_add_f32_e32 v65, 1.0, v65
	v_add_f32_e32 v60, 1.0, v60
	v_cndmask_b32_e64 v80, v80, v90, s[38:39]
	v_cndmask_b32_e32 v90, 0, v229, vcc
	v_sub_f32_e32 v80, v80, v90
	v_add_f32_e32 v80, v81, v80
	v_sub_f32_e32 v80, -0.5, v80
	v_mul_f32_e32 v80, 0x3fb8aa3b, v80
	v_exp_f32_e32 v80, v80
	v_max_f32_e64 v81, -v130, -v130
	v_add_f32_e32 v61, 1.0, v61
	v_add_f32_e32 v70, v70, v126
	v_mul_f32_e32 v80, 0xbfb8aa3b, v80
	v_exp_f32_e32 v90, v80
	v_add_f32_e32 v80, v86, v134
	v_mul_f32_e32 v80, 0xbfb8aa3b, v80
	v_exp_f32_e32 v80, v80
	v_add_f32_e32 v71, v71, v127
	v_add_f32_e32 v66, v66, v122
	v_add_f32_e32 v67, v67, v123
	v_add_f32_e32 v80, 1.0, v80
	v_rcp_f32_e32 v86, v80
	v_add_f32_e32 v80, v82, v138
	v_max_f32_e32 v82, 0, v81
	v_mul_f32_e64 v81, |v130|, s0
	v_exp_f32_e32 v81, v81
	v_mul_f32_e32 v80, 0xbfb8aa3b, v80
	v_exp_f32_e32 v80, v80
	v_mul_f32_e32 v66, 0xbfb8aa3b, v66
	v_add_f32_e32 v81, 1.0, v81
	v_cmp_gt_f32_e32 vcc, s33, v81
	v_add_f32_e32 v80, 1.0, v80
	v_rcp_f32_e32 v80, v80
	v_cndmask_b32_e64 v130, 0, 32, vcc
	v_ldexp_f32 v81, v81, v130
	v_log_f32_e32 v81, v81
	v_mul_f32_e32 v67, 0xbfb8aa3b, v67
	v_exp_f32_e32 v66, v66
	v_exp_f32_e32 v67, v67
	v_mul_f32_e32 v130, 0x3f317217, v81
	v_fma_f32 v130, v81, s2, -v130
	v_fmac_f32_e32 v130, 0x3377d1cf, v81
	v_fmac_f32_e32 v130, 0x3f317217, v81
	v_cmp_lt_f32_e64 s[38:39], |v81|, s1
	v_add_f32_e32 v66, 1.0, v66
	v_add_f32_e32 v67, 1.0, v67
	v_cndmask_b32_e64 v81, v81, v130, s[38:39]
	v_cndmask_b32_e32 v130, 0, v229, vcc
	v_sub_f32_e32 v130, v81, v130
	v_add_f32_e32 v81, v91, v143
	v_max_f32_e64 v91, -v81, 0
	v_mul_f32_e64 v81, |v81|, s0
	v_exp_f32_e32 v81, v81
	v_rcp_f32_e32 v66, v66
	v_rcp_f32_e32 v67, v67
	v_add_f32_e32 v62, v62, v118
	v_add_f32_e32 v81, 1.0, v81
	v_cmp_gt_f32_e32 vcc, s33, v81
	v_pk_mul_f32 v[66:67], v[66:67], s[6:7] op_sel_hi:[1,0]
	v_add_f32_e32 v63, v63, v119
	v_cndmask_b32_e64 v132, 0, 32, vcc
	v_ldexp_f32 v81, v81, v132
	v_log_f32_e32 v81, v81
	v_mul_f32_e32 v62, 0xbfb8aa3b, v62
	v_mul_f32_e32 v63, 0xbfb8aa3b, v63
	v_exp_f32_e32 v62, v62
	v_mul_f32_e32 v132, 0x3f317217, v81
	v_fma_f32 v132, v81, s2, -v132
	v_fmac_f32_e32 v132, 0x3377d1cf, v81
	v_fmac_f32_e32 v132, 0x3f317217, v81
	v_cmp_lt_f32_e64 s[38:39], |v81|, s1
	v_exp_f32_e32 v63, v63
	v_add_f32_e32 v62, 1.0, v62
	v_cndmask_b32_e64 v81, v81, v132, s[38:39]
	v_cndmask_b32_e32 v132, 0, v229, vcc
	v_sub_f32_e32 v81, v81, v132
	v_add_f32_e32 v81, v91, v81
	v_sub_f32_e32 v81, -0.5, v81
	v_mul_f32_e32 v81, 0x3fb8aa3b, v81
	v_exp_f32_e32 v81, v81
	v_pk_mul_f32 v[132:133], v[196:197], v[148:149] op_sel_hi:[1,0]
	v_add_f32_e32 v63, 1.0, v63
	v_rcp_f32_e32 v62, v62
	v_mul_f32_e32 v81, 0xbfb8aa3b, v81
	v_exp_f32_e32 v91, v81
	v_add_f32_e32 v81, v87, v135
	v_mul_f32_e32 v81, 0xbfb8aa3b, v81
	v_exp_f32_e32 v81, v81
	v_pk_add_f32 v[136:137], v[90:91], 1.0 op_sel_hi:[1,0] neg_lo:[1,0] neg_hi:[1,0]
	v_pk_mul_f32 v[90:91], v[194:195], v[132:133]
	v_cvt_pk_bf16_f32 v135, v136, v137
	v_add_f32_e32 v81, 1.0, v81
	v_rcp_f32_e32 v87, v81
	v_add_f32_e32 v81, v83, v139
	v_max_f32_e64 v83, -v131, -v131
	v_mul_f32_e64 v131, |v131|, s0
	v_exp_f32_e32 v131, v131
	v_max_f32_e32 v83, 0, v83
	v_pk_mul_f32 v[86:87], v[86:87], s[6:7] op_sel_hi:[1,0]
	v_mul_f32_e32 v81, 0xbfb8aa3b, v81
	v_add_f32_e32 v131, 1.0, v131
	v_cmp_gt_f32_e32 vcc, s33, v131
	v_exp_f32_e32 v81, v81
	v_cvt_pk_bf16_f32 v89, v90, v91
	v_cndmask_b32_e64 v134, 0, 32, vcc
	v_ldexp_f32 v131, v131, v134
	v_log_f32_e32 v131, v131
	v_add_f32_e32 v81, 1.0, v81
	v_rcp_f32_e32 v81, v81
	v_rcp_f32_e32 v90, v64
	v_mul_f32_e32 v134, 0x3f317217, v131
	v_fma_f32 v134, v131, s2, -v134
	v_fmac_f32_e32 v134, 0x3377d1cf, v131
	v_fmac_f32_e32 v134, 0x3f317217, v131
	v_cmp_lt_f32_e64 s[38:39], |v131|, s1
	v_pk_mul_f32 v[80:81], v[80:81], v[144:145]
	v_rcp_f32_e32 v91, v65
	v_cndmask_b32_e64 v131, v131, v134, s[38:39]
	v_cndmask_b32_e32 v134, 0, v229, vcc
	v_sub_f32_e32 v131, v131, v134
	v_pk_add_f32 v[82:83], v[82:83], v[130:131]
	v_rcp_f32_e32 v64, v60
	v_pk_mul_f32 v[82:83], v[86:87], v[82:83]
	s_waitcnt vmcnt(8)
; __device__ __forceinline__ float sigmoidf_(float x) { return __builtin_amdgcn_rcpf(1.f + __expf(-x)); }
; __device__ __forceinline__ float softplus_fast(float x) { return fmaxf(x, 0.f) + __logf(1.f + __expf(-fabsf(x))); }
; __device__ __forceinline__ void prep_unit(CP p, int l, int u, char* smem) {
;     ...
;       for (int j = 0; j < 4; ++j) {
;         const int x = mf * 4 + j;
;         const float wv = w0_[j] + accw[mf][j];
;         const float w = -softplus_fast(-wv) - 0.5f;
;         omw[j] = 1.f - __expf(-__expf(w));
;         kn[j] = kkv[x] * inv;
;         bb[j] = kn[j] * avv[x];
;         const float rr = sigmoidf_(accr[mf][j] + ba_[j]), ii = sigmoidf_(acci[mf][j] + bx_[j]);
;         la[j] = -8.f * rr * softplus_fast(-lam_[j]);
;         uu[j] = sqrtf(fmaxf(1.f - __expf(2.f * la[j]), 0.f)) * (ii * xc_[j]);
;       }
;       bf16_t* o = RW + row * 1536 + c;
;       *reinterpret_cast<uint2*>(o) = make_uint2(pack2(omw[0], omw[1]), pack2(omw[2], omw[3]));
;       *reinterpret_cast<uint2*>(o + 256) = make_uint2(pack2(kn[0], kn[1]), pack2(kn[2], kn[3]));
;       *reinterpret_cast<uint2*>(o + 512) = make_uint2(pack2(bb[0], bb[1]), pack2(bb[2], bb[3]));
;       *reinterpret_cast<uint2*>(o + 768) = make_uint2(pack2(kpv[mf * 4], kpv[mf * 4 + 1]), pack2(kpv[mf * 4 + 2], kpv[mf * 4 + 3]));
;       *reinterpret_cast<uint2*>(o + 1024) = make_uint2(pack2(rv[mf * 4], rv[mf * 4 + 1]), pack2(rv[mf * 4 + 2], rv[mf * 4 + 3]));
;       *reinterpret_cast<uint2*>(RG + row * 256 + c) = make_uint2(pack2(accg[mf][0], accg[mf][1]), pack2(accg[mf][2], accg[mf][3]));
;       *reinterpret_cast<uint2*>(LR + row * 512 + c) = make_uint2(pack2(la[0], la[1]), pack2(la[2], la[3]));
;       *reinterpret_cast<uint2*>(LR + row * 512 + 256 + c) = make_uint2(pack2(uu[0], uu[1]), pack2(uu[2], uu[3]));
	v_max_f32_e64 v60, -v112, -v112
	v_add_f32_e32 v86, v82, v82
	v_mul_f32_e32 v86, 0x3fb8aa3b, v86
	v_exp_f32_e32 v86, v86
	v_cvt_pk_bf16_f32 v85, v82, v83
	v_rcp_f32_e32 v65, v61
	v_max_f32_e64 v61, -v113, -v113
	v_sub_f32_e32 v86, 1.0, v86
	v_max_f32_e32 v86, 0, v86
	v_cmp_gt_f32_e32 vcc, s4, v86
	v_mul_f32_e32 v87, 0x4f800000, v86
	v_max_f32_e32 v60, 0, v60
	v_cndmask_b32_e32 v86, v86, v87, vcc
	v_sqrt_f32_e32 v87, v86
	v_max_f32_e32 v61, 0, v61
	v_pk_mul_f32 v[90:91], v[90:91], s[6:7] op_sel_hi:[1,0]
	v_rcp_f32_e32 v63, v63
	v_add_u32_e32 v130, -1, v87
	v_fma_f32 v131, -v130, v87, v86
	v_cmp_ge_f32_e64 s[38:39], 0, v131
	v_add_u32_e32 v131, 1, v87
	v_cvt_pk_bf16_f32 v82, v128, v129
	v_cndmask_b32_e64 v130, v87, v130, s[38:39]
	v_fma_f32 v87, -v131, v87, v86
	v_cmp_lt_f32_e64 s[38:39], 0, v87
	v_cvt_pk_bf16_f32 v40, v40, v41
	v_cvt_pk_bf16_f32 v41, v42, v43
	v_cndmask_b32_e64 v87, v130, v131, s[38:39]
	v_mul_f32_e32 v130, 0x37800000, v87
	v_cndmask_b32_e32 v87, v87, v130, vcc
	v_cmp_class_f32_e32 vcc, v86, v218
	s_waitcnt vmcnt(7)
	v_add_f32_e32 v32, v32, v104
	v_add_f32_e32 v33, v33, v105
	v_cndmask_b32_e32 v86, v87, v86, vcc
	v_add_f32_e32 v87, v83, v83
	v_mul_f32_e32 v87, 0x3fb8aa3b, v87
	v_exp_f32_e32 v87, v87
	s_waitcnt vmcnt(6)
	v_add_f32_e32 v28, v28, v100
	v_add_f32_e32 v29, v29, v101
	v_mul_f32_e32 v28, 0xbfb8aa3b, v28
	v_sub_f32_e32 v87, 1.0, v87
	v_max_f32_e32 v87, 0, v87
	v_cmp_gt_f32_e32 vcc, s4, v87
	v_mul_f32_e32 v130, 0x4f800000, v87
	v_mul_f32_e32 v29, 0xbfb8aa3b, v29
	v_cndmask_b32_e32 v87, v87, v130, vcc
	v_sqrt_f32_e32 v130, v87
	v_exp_f32_e32 v28, v28
	s_waitcnt vmcnt(5)
	v_add_f32_e32 v24, v24, v96
	v_exp_f32_e32 v29, v29
	v_add_u32_e32 v131, -1, v130
	v_fma_f32 v134, -v131, v130, v87
	v_cmp_ge_f32_e64 s[38:39], 0, v134
	v_add_u32_e32 v134, 1, v130
	v_add_f32_e32 v25, v25, v97
	v_cndmask_b32_e64 v131, v130, v131, s[38:39]
	v_fma_f32 v130, -v134, v130, v87
	v_cmp_lt_f32_e64 s[38:39], 0, v130
	v_mul_f32_e32 v24, 0xbfb8aa3b, v24
	v_mul_f32_e32 v25, 0xbfb8aa3b, v25
	v_cndmask_b32_e64 v130, v131, v134, s[38:39]
	v_mul_f32_e32 v131, 0x37800000, v130
	v_cndmask_b32_e32 v130, v130, v131, vcc
	v_cmp_class_f32_e32 vcc, v87, v218
	v_cvt_pk_bf16_f32 v134, v208, v209
	v_exp_f32_e32 v24, v24
	v_cndmask_b32_e32 v87, v130, v87, vcc
	v_lshlrev_b64 v[130:131], 1, v[186:187]
	v_pk_mul_f32 v[86:87], v[86:87], v[80:81]
	v_lshl_add_u64 v[80:81], v[206:207], 0, v[130:131]
	global_store_dwordx2 v[80:81], v[88:89], off offset:1024
	v_cvt_pk_bf16_f32 v88, v190, v191
	v_cvt_pk_bf16_f32 v89, v192, v193
	global_store_dwordx2 v[80:81], v[134:135], off
	v_cvt_pk_bf16_f32 v134, v140, v141
	v_cvt_pk_bf16_f32 v135, v132, v133
	global_store_dwordx2 v[80:81], v[88:89], off offset:1536
	v_cvt_pk_bf16_f32 v88, v108, v109
	v_cvt_pk_bf16_f32 v89, v110, v111
	v_lshl_add_u64 v[78:79], v[204:205], 0, v[130:131]
	global_store_dwordx2 v[80:81], v[134:135], off offset:512
	global_store_dwordx2 v[80:81], v[88:89], off offset:2048
	global_store_dwordx2 v[78:79], v[76:77], off
	v_lshl_add_u64 v[76:77], v[202:203], 0, v[130:131]
	global_store_dwordx2 v[76:77], v[84:85], off
	v_max_f32_e64 v84, -v68, 0
	v_mul_f32_e64 v68, |v68|, s0
	v_exp_f32_e32 v68, v68
	v_mul_f32_e64 v109, |v113|, s0
	v_exp_f32_e32 v109, v109
	v_lshlrev_b32_e32 v88, 16, v146
	v_add_f32_e32 v68, 1.0, v68
	v_cmp_gt_f32_e32 vcc, s33, v68
	v_add_f32_e32 v109, 1.0, v109
	v_and_b32_e32 v89, 0xffff0000, v146
	v_cndmask_b32_e64 v85, 0, 32, vcc
	v_ldexp_f32 v68, v68, v85
	v_log_f32_e32 v68, v68
	v_pk_mul_f32 v[64:65], v[64:65], v[88:89]
	v_max_f32_e64 v88, -v70, 0
	v_mul_f32_e64 v70, |v70|, s0
	v_mul_f32_e32 v85, 0x3f317217, v68
	v_fma_f32 v85, v68, s2, -v85
	v_fmac_f32_e32 v85, 0x3377d1cf, v68
	v_fmac_f32_e32 v85, 0x3f317217, v68
	v_cmp_lt_f32_e64 s[38:39], |v68|, s1
	v_exp_f32_e32 v70, v70
	v_cvt_pk_bf16_f32 v83, v86, v87
	v_cndmask_b32_e64 v68, v68, v85, s[38:39]
	v_cndmask_b32_e32 v85, 0, v229, vcc
	v_sub_f32_e32 v68, v68, v85
	v_add_f32_e32 v68, v84, v68
	v_mul_f32_e64 v84, |v112|, s0
	v_exp_f32_e32 v84, v84
	v_add_f32_e32 v70, 1.0, v70
	v_sub_f32_e32 v68, -0.5, v68
	v_mul_f32_e32 v68, 0x3fb8aa3b, v68
	v_add_f32_e32 v84, 1.0, v84
	v_cmp_gt_f32_e32 vcc, s33, v84
	v_exp_f32_e32 v68, v68
	global_store_dwordx2 v[76:77], v[82:83], off offset:512
	v_cndmask_b32_e64 v85, 0, 32, vcc
	v_ldexp_f32 v84, v84, v85
	v_log_f32_e32 v84, v84
	v_mul_f32_e32 v68, 0xbfb8aa3b, v68
	v_exp_f32_e32 v68, v68
	v_lshlrev_b32_e32 v82, 16, v147
	v_mul_f32_e32 v85, 0x3f317217, v84
	v_fma_f32 v85, v84, s2, -v85
	v_fmac_f32_e32 v85, 0x3377d1cf, v84
	v_fmac_f32_e32 v85, 0x3f317217, v84
	v_cmp_lt_f32_e64 s[38:39], |v84|, s1
	v_and_b32_e32 v83, 0xffff0000, v147
	v_pk_mul_f32 v[62:63], v[62:63], v[82:83]
	v_cndmask_b32_e64 v84, v84, v85, s[38:39]
	v_cndmask_b32_e32 v85, 0, v229, vcc
	v_sub_f32_e32 v108, v84, v85
	v_max_f32_e64 v84, -v69, 0
	v_mul_f32_e64 v69, |v69|, s0
	v_exp_f32_e32 v69, v69
	v_exp_f32_e32 v25, v25
	v_add_f32_e32 v28, 1.0, v28
	v_add_f32_e32 v29, 1.0, v29
	v_add_f32_e32 v69, 1.0, v69
	v_cmp_gt_f32_e32 vcc, s33, v69
	v_add_f32_e32 v24, 1.0, v24
	v_add_f32_e32 v25, 1.0, v25
	v_cndmask_b32_e64 v85, 0, 32, vcc
	v_ldexp_f32 v69, v69, v85
	v_log_f32_e32 v69, v69
	v_add_f32_e32 v34, v34, v106
	v_add_f32_e32 v35, v35, v107
	v_add_f32_e32 v30, v30, v102
	v_mul_f32_e32 v85, 0x3f317217, v69
	v_fma_f32 v85, v69, s2, -v85
	v_fmac_f32_e32 v85, 0x3377d1cf, v69
	v_fmac_f32_e32 v85, 0x3f317217, v69
	v_cmp_lt_f32_e64 s[38:39], |v69|, s1
	v_add_f32_e32 v31, v31, v103
	v_mul_f32_e32 v30, 0xbfb8aa3b, v30
	v_cndmask_b32_e64 v69, v69, v85, s[38:39]
	v_cndmask_b32_e32 v85, 0, v229, vcc
	v_cmp_gt_f32_e32 vcc, s33, v109
	v_sub_f32_e32 v69, v69, v85
; __device__ __forceinline__ float sigmoidf_(float x) { return __builtin_amdgcn_rcpf(1.f + __expf(-x)); }
; __device__ __forceinline__ float softplus_fast(float x) { return fmaxf(x, 0.f) + __logf(1.f + __expf(-fabsf(x))); }
; __device__ __forceinline__ void prep_unit(CP p, int l, int u, char* smem) {
;     ...
;       for (int j = 0; j < 4; ++j) {
;         const int x = mf * 4 + j;
;         const float wv = w0_[j] + accw[mf][j];
;         const float w = -softplus_fast(-wv) - 0.5f;
;         omw[j] = 1.f - __expf(-__expf(w));
;         kn[j] = kkv[x] * inv;
;         bb[j] = kn[j] * avv[x];
;         const float rr = sigmoidf_(accr[mf][j] + ba_[j]), ii = sigmoidf_(acci[mf][j] + bx_[j]);
;         la[j] = -8.f * rr * softplus_fast(-lam_[j]);
;         uu[j] = sqrtf(fmaxf(1.f - __expf(2.f * la[j]), 0.f)) * (ii * xc_[j]);
	v_add_f32_e32 v69, v84, v69
	v_cndmask_b32_e64 v110, 0, 32, vcc
	v_ldexp_f32 v109, v109, v110
	v_log_f32_e32 v109, v109
	v_sub_f32_e32 v69, -0.5, v69
	v_mul_f32_e32 v69, 0x3fb8aa3b, v69
	v_exp_f32_e32 v69, v69
	v_mul_f32_e32 v110, 0x3f317217, v109
	v_fma_f32 v110, v109, s2, -v110
	v_fmac_f32_e32 v110, 0x3377d1cf, v109
	v_fmac_f32_e32 v110, 0x3f317217, v109
	v_cmp_lt_f32_e64 s[38:39], |v109|, s1
	v_mul_f32_e32 v69, 0xbfb8aa3b, v69
	v_exp_f32_e32 v69, v69
	v_cndmask_b32_e64 v109, v109, v110, s[38:39]
	v_cndmask_b32_e32 v110, 0, v229, vcc
	v_sub_f32_e32 v109, v109, v110
	v_pk_add_f32 v[60:61], v[60:61], v[108:109]
	v_pk_mul_f32 v[84:85], v[188:189], v[148:149] op_sel_hi:[1,0]
	v_pk_mul_f32 v[60:61], v[90:91], v[60:61]
	v_pk_add_f32 v[86:87], v[68:69], 1.0 op_sel_hi:[1,0] neg_lo:[1,0] neg_hi:[1,0]
	v_add_f32_e32 v90, v60, v60
	v_mul_f32_e32 v90, 0x3fb8aa3b, v90
	v_exp_f32_e32 v90, v90
	v_pk_mul_f32 v[68:69], v[184:185], v[84:85]
	v_mul_f32_e32 v31, 0xbfb8aa3b, v31
	v_cvt_pk_bf16_f32 v68, v68, v69
	v_sub_f32_e32 v90, 1.0, v90
	v_max_f32_e32 v90, 0, v90
	v_cmp_gt_f32_e32 vcc, s4, v90
	v_mul_f32_e32 v91, 0x4f800000, v90
	v_exp_f32_e32 v30, v30
	v_cndmask_b32_e32 v90, v90, v91, vcc
	v_sqrt_f32_e32 v91, v90
	v_exp_f32_e32 v31, v31
	v_add_f32_e32 v30, 1.0, v30
	v_rcp_f32_e32 v30, v30
	v_add_u32_e32 v108, -1, v91
	v_fma_f32 v109, -v108, v91, v90
	v_cmp_ge_f32_e64 s[38:39], 0, v109
	v_add_u32_e32 v109, 1, v91
	v_add_f32_e32 v31, 1.0, v31
	v_cndmask_b32_e64 v108, v91, v108, s[38:39]
	v_fma_f32 v91, -v109, v91, v90
	v_cmp_lt_f32_e64 s[38:39], 0, v91
	v_rcp_f32_e32 v31, v31
	s_waitcnt vmcnt(11)
	v_add_f32_e32 v12, v12, v56
	v_cndmask_b32_e64 v91, v108, v109, s[38:39]
	v_mul_f32_e32 v108, 0x37800000, v91
	v_cndmask_b32_e32 v91, v91, v108, vcc
	v_cmp_class_f32_e32 vcc, v90, v218
	v_pk_mul_f32 v[30:31], v[30:31], s[6:7] op_sel_hi:[1,0]
	v_cvt_pk_bf16_f32 v16, v16, v17
	v_cndmask_b32_e32 v90, v91, v90, vcc
	v_add_f32_e32 v91, v61, v61
	v_mul_f32_e32 v91, 0x3fb8aa3b, v91
	v_exp_f32_e32 v91, v91
	v_cvt_pk_bf16_f32 v17, v18, v19
	v_max_f32_e64 v18, -v12, 0
	v_mul_f32_e64 v12, |v12|, s0
	v_sub_f32_e32 v91, 1.0, v91
	v_max_f32_e32 v91, 0, v91
	v_cmp_gt_f32_e32 vcc, s4, v91
	v_mul_f32_e32 v108, 0x4f800000, v91
	v_exp_f32_e32 v12, v12
	v_cndmask_b32_e32 v91, v91, v108, vcc
	v_sqrt_f32_e32 v108, v91
	v_add_f32_e32 v26, v26, v98
	v_add_f32_e32 v12, 1.0, v12
	v_add_f32_e32 v27, v27, v99
	v_add_u32_e32 v109, -1, v108
	v_fma_f32 v110, -v109, v108, v91
	v_cmp_ge_f32_e64 s[38:39], 0, v110
	v_add_u32_e32 v110, 1, v108
	v_mul_f32_e32 v26, 0xbfb8aa3b, v26
	v_cndmask_b32_e64 v109, v108, v109, s[38:39]
	v_fma_f32 v108, -v110, v108, v91
	v_cmp_lt_f32_e64 s[38:39], 0, v108
	v_mul_f32_e32 v27, 0xbfb8aa3b, v27
	v_exp_f32_e32 v26, v26
	v_cndmask_b32_e64 v108, v109, v110, s[38:39]
	v_mul_f32_e32 v109, 0x37800000, v108
	v_cndmask_b32_e32 v108, v108, v109, vcc
	v_cmp_class_f32_e32 vcc, v91, v218
	v_mul_f32_e64 v109, |v115|, s0
	v_exp_f32_e32 v109, v109
	v_cndmask_b32_e32 v91, v108, v91, vcc
	v_cmp_gt_f32_e32 vcc, s33, v70
	v_pk_mul_f32 v[64:65], v[90:91], v[64:65]
	v_add_f32_e32 v109, 1.0, v109
	v_cndmask_b32_e64 v89, 0, 32, vcc
	v_ldexp_f32 v70, v70, v89
	v_log_f32_e32 v70, v70
	v_exp_f32_e32 v27, v27
	v_add_f32_e32 v26, 1.0, v26
	v_rcp_f32_e32 v26, v26
	v_mul_f32_e32 v89, 0x3f317217, v70
	v_fma_f32 v89, v70, s2, -v89
	v_fmac_f32_e32 v89, 0x3377d1cf, v70
	v_fmac_f32_e32 v89, 0x3f317217, v70
	v_cmp_lt_f32_e64 s[38:39], |v70|, s1
	v_add_f32_e32 v27, 1.0, v27
	v_rcp_f32_e32 v27, v27
	v_cndmask_b32_e64 v70, v70, v89, s[38:39]
	v_cndmask_b32_e32 v89, 0, v229, vcc
	v_sub_f32_e32 v70, v70, v89
	v_mul_f32_e64 v89, |v114|, s0
	v_exp_f32_e32 v89, v89
	v_add_f32_e32 v70, v88, v70
	v_sub_f32_e32 v70, -0.5, v70
	v_mul_f32_e32 v70, 0x3fb8aa3b, v70
	v_add_f32_e32 v89, 1.0, v89
	v_cmp_gt_f32_e32 vcc, s33, v89
	v_exp_f32_e32 v70, v70
	v_add_f32_e32 v13, v13, v57
	v_cndmask_b32_e64 v90, 0, 32, vcc
	v_ldexp_f32 v89, v89, v90
	v_log_f32_e32 v89, v89
	v_mul_f32_e32 v70, 0xbfb8aa3b, v70
	v_exp_f32_e32 v88, v70
	v_max_f32_e64 v70, -v114, -v114
	v_mul_f32_e32 v90, 0x3f317217, v89
	v_fma_f32 v90, v89, s2, -v90
	v_fmac_f32_e32 v90, 0x3377d1cf, v89
	v_fmac_f32_e32 v90, 0x3f317217, v89
	v_cmp_lt_f32_e64 s[38:39], |v89|, s1
	v_max_f32_e32 v70, 0, v70
	s_waitcnt vmcnt(10)
	v_add_f32_e32 v8, v8, v52
	v_cndmask_b32_e64 v89, v89, v90, s[38:39]
	v_cndmask_b32_e32 v90, 0, v229, vcc
	v_sub_f32_e32 v108, v89, v90
	v_max_f32_e64 v89, -v71, 0
	v_mul_f32_e64 v71, |v71|, s0
	v_exp_f32_e32 v71, v71
	v_add_f32_e32 v9, v9, v53
	v_mul_f32_e32 v8, 0xbfb8aa3b, v8
	v_mul_f32_e32 v9, 0xbfb8aa3b, v9
	v_add_f32_e32 v71, 1.0, v71
	v_cmp_gt_f32_e32 vcc, s33, v71
	v_exp_f32_e32 v8, v8
	s_waitcnt vmcnt(9)
; __device__ __forceinline__ float sigmoidf_(float x) { return __builtin_amdgcn_rcpf(1.f + __expf(-x)); }
; __device__ __forceinline__ float softplus_fast(float x) { return fmaxf(x, 0.f) + __logf(1.f + __expf(-fabsf(x))); }
; __device__ __forceinline__ void prep_unit(CP p, int l, int u, char* smem) {
;     ...
;       for (int j = 0; j < 4; ++j) {
;         const int x = mf * 4 + j;
;         const float wv = w0_[j] + accw[mf][j];
;         const float w = -softplus_fast(-wv) - 0.5f;
;         omw[j] = 1.f - __expf(-__expf(w));
;         kn[j] = kkv[x] * inv;
;         bb[j] = kn[j] * avv[x];
;         const float rr = sigmoidf_(accr[mf][j] + ba_[j]), ii = sigmoidf_(acci[mf][j] + bx_[j]);
;         la[j] = -8.f * rr * softplus_fast(-lam_[j]);
;         uu[j] = sqrtf(fmaxf(1.f - __expf(2.f * la[j]), 0.f)) * (ii * xc_[j]);
;       }
;       bf16_t* o = RW + row * 1536 + c;
;       *reinterpret_cast<uint2*>(o) = make_uint2(pack2(omw[0], omw[1]), pack2(omw[2], omw[3]));
;       *reinterpret_cast<uint2*>(o + 256) = make_uint2(pack2(kn[0], kn[1]), pack2(kn[2], kn[3]));
;       *reinterpret_cast<uint2*>(o + 512) = make_uint2(pack2(bb[0], bb[1]), pack2(bb[2], bb[3]));
;       *reinterpret_cast<uint2*>(o + 768) = make_uint2(pack2(kpv[mf * 4], kpv[mf * 4 + 1]), pack2(kpv[mf * 4 + 2], kpv[mf * 4 + 3]));
;       *reinterpret_cast<uint2*>(o + 1024) = make_uint2(pack2(rv[mf * 4], rv[mf * 4 + 1]), pack2(rv[mf * 4 + 2], rv[mf * 4 + 3]));
;       *reinterpret_cast<uint2*>(RG + row * 256 + c) = make_uint2(pack2(accg[mf][0], accg[mf][1]), pack2(accg[mf][2], accg[mf][3]));
;       *reinterpret_cast<uint2*>(LR + row * 512 + c) = make_uint2(pack2(la[0], la[1]), pack2(la[2], la[3]));
;       *reinterpret_cast<uint2*>(LR + row * 512 + 256 + c) = make_uint2(pack2(uu[0], uu[1]), pack2(uu[2], uu[3]));
	v_add_f32_e32 v4, v4, v48
	v_cndmask_b32_e64 v90, 0, 32, vcc
	v_ldexp_f32 v71, v71, v90
	v_log_f32_e32 v71, v71
	v_exp_f32_e32 v9, v9
	v_add_f32_e32 v5, v5, v49
	v_mul_f32_e32 v4, 0xbfb8aa3b, v4
	v_mul_f32_e32 v90, 0x3f317217, v71
	v_fma_f32 v90, v71, s2, -v90
	v_fmac_f32_e32 v90, 0x3377d1cf, v71
	v_fmac_f32_e32 v90, 0x3f317217, v71
	v_cmp_lt_f32_e64 s[38:39], |v71|, s1
	v_mul_f32_e32 v5, 0xbfb8aa3b, v5
	v_exp_f32_e32 v4, v4
	v_cndmask_b32_e64 v71, v71, v90, s[38:39]
	v_cndmask_b32_e32 v90, 0, v229, vcc
	v_cmp_gt_f32_e32 vcc, s33, v109
	v_sub_f32_e32 v71, v71, v90
	v_add_f32_e32 v71, v89, v71
	v_cndmask_b32_e64 v112, 0, 32, vcc
	v_ldexp_f32 v109, v109, v112
	v_log_f32_e32 v109, v109
	v_sub_f32_e32 v71, -0.5, v71
	v_mul_f32_e32 v71, 0x3fb8aa3b, v71
	v_exp_f32_e32 v71, v71
	v_mul_f32_e32 v112, 0x3f317217, v109
	v_fma_f32 v112, v109, s2, -v112
	v_fmac_f32_e32 v112, 0x3377d1cf, v109
	v_mul_f32_e32 v71, 0xbfb8aa3b, v71
	v_fmac_f32_e32 v112, 0x3f317217, v109
	v_cmp_lt_f32_e64 s[38:39], |v109|, s1
	v_exp_f32_e32 v89, v71
	v_max_f32_e64 v71, -v115, -v115
	v_cndmask_b32_e64 v109, v109, v112, s[38:39]
	v_cndmask_b32_e32 v112, 0, v229, vcc
	v_max_f32_e32 v71, 0, v71
	v_sub_f32_e32 v109, v109, v112
	v_pk_add_f32 v[70:71], v[70:71], v[108:109]
	v_pk_mul_f32 v[90:91], v[182:183], v[148:149] op_sel_hi:[1,0]
	v_pk_mul_f32 v[66:67], v[66:67], v[70:71]
	v_pk_add_f32 v[110:111], v[88:89], 1.0 op_sel_hi:[1,0] neg_lo:[1,0] neg_hi:[1,0]
	v_add_f32_e32 v70, v66, v66
	v_mul_f32_e32 v70, 0x3fb8aa3b, v70
	v_exp_f32_e32 v70, v70
	v_pk_mul_f32 v[88:89], v[180:181], v[90:91]
	v_exp_f32_e32 v5, v5
	v_cvt_pk_bf16_f32 v69, v88, v89
	v_sub_f32_e32 v70, 1.0, v70
	v_max_f32_e32 v70, 0, v70
	v_cmp_gt_f32_e32 vcc, s4, v70
	v_mul_f32_e32 v71, 0x4f800000, v70
	global_store_dwordx2 v[80:81], v[68:69], off offset:1056
	v_cndmask_b32_e32 v70, v70, v71, vcc
	v_sqrt_f32_e32 v71, v70
	v_cvt_pk_bf16_f32 v68, v174, v175
	v_cvt_pk_bf16_f32 v69, v178, v179
	global_store_dwordx2 v[80:81], v[68:69], off offset:1568
	v_add_u32_e32 v108, -1, v71
	v_fma_f32 v109, -v108, v71, v70
	v_cmp_ge_f32_e64 s[38:39], 0, v109
	v_add_u32_e32 v109, 1, v71
	v_cvt_pk_bf16_f32 v68, v72, v73
	v_cndmask_b32_e64 v108, v71, v108, s[38:39]
	v_fma_f32 v71, -v109, v71, v70
	v_cmp_lt_f32_e64 s[38:39], 0, v71
	v_cvt_pk_bf16_f32 v69, v74, v75
	global_store_dwordx2 v[80:81], v[68:69], off offset:2080
	v_cndmask_b32_e64 v71, v108, v109, s[38:39]
	v_mul_f32_e32 v108, 0x37800000, v71
	v_cndmask_b32_e32 v71, v71, v108, vcc
	v_cmp_class_f32_e32 vcc, v70, v218
	v_mul_f32_e64 v69, |v93|, s0
	v_exp_f32_e32 v69, v69
	v_cndmask_b32_e32 v70, v71, v70, vcc
	v_add_f32_e32 v71, v67, v67
	v_mul_f32_e32 v71, 0x3fb8aa3b, v71
	v_exp_f32_e32 v71, v71
	v_add_f32_e32 v69, 1.0, v69
	v_add_f32_e32 v8, 1.0, v8
	v_add_f32_e32 v9, 1.0, v9
	v_sub_f32_e32 v71, 1.0, v71
	v_max_f32_e32 v71, 0, v71
	v_cmp_gt_f32_e32 vcc, s4, v71
	v_mul_f32_e32 v108, 0x4f800000, v71
	v_add_f32_e32 v4, 1.0, v4
	v_cndmask_b32_e32 v71, v71, v108, vcc
	v_sqrt_f32_e32 v108, v71
	v_add_f32_e32 v5, 1.0, v5
	v_add_f32_e32 v14, v14, v58
	v_add_f32_e32 v15, v15, v59
	v_add_u32_e32 v109, -1, v108
	v_fma_f32 v112, -v109, v108, v71
	v_cmp_ge_f32_e64 s[38:39], 0, v112
	v_add_u32_e32 v112, 1, v108
	v_add_f32_e32 v10, v10, v54
	v_cndmask_b32_e64 v109, v108, v109, s[38:39]
	v_fma_f32 v108, -v112, v108, v71
	v_cmp_lt_f32_e64 s[38:39], 0, v108
	v_add_f32_e32 v11, v11, v55
	v_mul_f32_e32 v10, 0xbfb8aa3b, v10
	v_cndmask_b32_e64 v108, v109, v112, s[38:39]
	v_mul_f32_e32 v109, 0x37800000, v108
	v_cndmask_b32_e32 v108, v108, v109, vcc
	v_cmp_class_f32_e32 vcc, v71, v218
	v_mul_f32_e32 v11, 0xbfb8aa3b, v11
	v_exp_f32_e32 v10, v10
	v_cndmask_b32_e32 v71, v108, v71, vcc
	v_pk_mul_f32 v[62:63], v[70:71], v[62:63]
	v_cvt_pk_bf16_f32 v70, v86, v87
	v_cvt_pk_bf16_f32 v71, v110, v111
	global_store_dwordx2 v[80:81], v[70:71], off offset:32
	v_cvt_pk_bf16_f32 v70, v84, v85
	v_cvt_pk_bf16_f32 v71, v90, v91
	global_store_dwordx2 v[80:81], v[70:71], off offset:544
	global_store_dwordx2 v[78:79], v[40:41], off offset:32
	v_cvt_pk_bf16_f32 v40, v60, v61
	v_max_f32_e64 v60, -v32, 0
	v_mul_f32_e64 v32, |v32|, s0
	v_exp_f32_e32 v32, v32
	v_cvt_pk_bf16_f32 v41, v66, v67
	v_rcp_f32_e32 v66, v28
	v_rcp_f32_e32 v67, v29
	v_add_f32_e32 v32, 1.0, v32
	v_cmp_gt_f32_e32 vcc, s33, v32
	v_rcp_f32_e32 v28, v24
	v_max_f32_e64 v24, -v92, -v92
	v_cndmask_b32_e64 v61, 0, 32, vcc
	v_ldexp_f32 v32, v32, v61
	v_log_f32_e32 v32, v32
	v_rcp_f32_e32 v29, v25
	v_max_f32_e64 v25, -v93, -v93
	v_max_f32_e32 v24, 0, v24
	v_mul_f32_e32 v61, 0x3f317217, v32
	v_fma_f32 v61, v32, s2, -v61
	v_fmac_f32_e32 v61, 0x3377d1cf, v32
	v_fmac_f32_e32 v61, 0x3f317217, v32
	v_cmp_lt_f32_e64 s[38:39], |v32|, s1
	v_max_f32_e32 v25, 0, v25
	v_pk_mul_f32 v[66:67], v[66:67], s[6:7] op_sel_hi:[1,0]
	v_cndmask_b32_e64 v32, v32, v61, s[38:39]
	v_cndmask_b32_e32 v61, 0, v229, vcc
	v_sub_f32_e32 v32, v32, v61
	v_add_f32_e32 v32, v60, v32
	v_mul_f32_e64 v60, |v92|, s0
	v_exp_f32_e32 v60, v60
	global_store_dwordx2 v[76:77], v[40:41], off offset:32
	v_cvt_pk_bf16_f32 v40, v64, v65
	v_cvt_pk_bf16_f32 v41, v62, v63
	v_add_f32_e32 v60, 1.0, v60
	v_cmp_gt_f32_e32 vcc, s33, v60
	global_store_dwordx2 v[76:77], v[40:41], off offset:544
	ds_read2_b64 v[40:43], v232 offset0:72 offset1:76
	v_cndmask_b32_e64 v61, 0, 32, vcc
	v_ldexp_f32 v60, v60, v61
	v_log_f32_e32 v60, v60
	v_sub_f32_e32 v32, -0.5, v32
	s_waitcnt lgkmcnt(0)
; __device__ __forceinline__ float sigmoidf_(float x) { return __builtin_amdgcn_rcpf(1.f + __expf(-x)); }
; __device__ __forceinline__ float softplus_fast(float x) { return fmaxf(x, 0.f) + __logf(1.f + __expf(-fabsf(x))); }
; __device__ __forceinline__ void prep_unit(CP p, int l, int u, char* smem) {
;     ...
;       for (int j = 0; j < 4; ++j) {
;         const int x = mf * 4 + j;
;         const float wv = w0_[j] + accw[mf][j];
;         const float w = -softplus_fast(-wv) - 0.5f;
;         omw[j] = 1.f - __expf(-__expf(w));
;         kn[j] = kkv[x] * inv;
;         bb[j] = kn[j] * avv[x];
;         const float rr = sigmoidf_(accr[mf][j] + ba_[j]), ii = sigmoidf_(acci[mf][j] + bx_[j]);
;         la[j] = -8.f * rr * softplus_fast(-lam_[j]);
;         uu[j] = sqrtf(fmaxf(1.f - __expf(2.f * la[j]), 0.f)) * (ii * xc_[j]);
;       }
;       bf16_t* o = RW + row * 1536 + c;
;       *reinterpret_cast<uint2*>(o) = make_uint2(pack2(omw[0], omw[1]), pack2(omw[2], omw[3]));
;       *reinterpret_cast<uint2*>(o + 256) = make_uint2(pack2(kn[0], kn[1]), pack2(kn[2], kn[3]));
;       *reinterpret_cast<uint2*>(o + 512) = make_uint2(pack2(bb[0], bb[1]), pack2(bb[2], bb[3]));
;       *reinterpret_cast<uint2*>(o + 768) = make_uint2(pack2(kpv[mf * 4], kpv[mf * 4 + 1]), pack2(kpv[mf * 4 + 2], kpv[mf * 4 + 3]));
;       *reinterpret_cast<uint2*>(o + 1024) = make_uint2(pack2(rv[mf * 4], rv[mf * 4 + 1]), pack2(rv[mf * 4 + 2], rv[mf * 4 + 3]));
;       *reinterpret_cast<uint2*>(RG + row * 256 + c) = make_uint2(pack2(accg[mf][0], accg[mf][1]), pack2(accg[mf][2], accg[mf][3]));
;       *reinterpret_cast<uint2*>(LR + row * 512 + c) = make_uint2(pack2(la[0], la[1]), pack2(la[2], la[3]));
;       *reinterpret_cast<uint2*>(LR + row * 512 + 256 + c) = make_uint2(pack2(uu[0], uu[1]), pack2(uu[2], uu[3]));
; __device__ __forceinline__ void run_phase(CP p, int ph, char* smem_full) {
;     ...
;       for (int u = vb; u < NB * 129; u += NVB) prep_unit(p, l, u, smem);
	v_lshlrev_b32_e32 v64, 16, v40
	v_and_b32_e32 v65, 0xffff0000, v40
	v_mul_f32_e32 v61, 0x3f317217, v60
	v_fma_f32 v61, v60, s2, -v61
	v_fmac_f32_e32 v61, 0x3377d1cf, v60
	v_fmac_f32_e32 v61, 0x3f317217, v60
	v_cmp_lt_f32_e64 s[38:39], |v60|, s1
	v_pk_mul_f32 v[28:29], v[28:29], v[64:65]
	v_max_f32_e64 v64, -v34, 0
	v_cndmask_b32_e64 v60, v60, v61, s[38:39]
	v_cndmask_b32_e32 v61, 0, v229, vcc
	v_sub_f32_e32 v68, v60, v61
	v_max_f32_e64 v60, -v33, 0
	v_mul_f32_e64 v33, |v33|, s0
	v_exp_f32_e32 v33, v33
	v_mul_f32_e64 v34, |v34|, s0
	v_exp_f32_e32 v34, v34
	v_mul_f32_e32 v32, 0x3fb8aa3b, v32
	v_add_f32_e32 v33, 1.0, v33
	v_cmp_gt_f32_e32 vcc, s33, v33
	v_add_f32_e32 v34, 1.0, v34
	v_exp_f32_e32 v32, v32
	v_cndmask_b32_e64 v61, 0, 32, vcc
	v_ldexp_f32 v33, v33, v61
	v_log_f32_e32 v33, v33
	v_mul_f32_e32 v32, 0xbfb8aa3b, v32
	v_exp_f32_e32 v32, v32
	v_lshlrev_b32_e32 v40, 16, v41
	v_mul_f32_e32 v61, 0x3f317217, v33
	v_fma_f32 v61, v33, s2, -v61
	v_fmac_f32_e32 v61, 0x3377d1cf, v33
	v_fmac_f32_e32 v61, 0x3f317217, v33
	v_cmp_lt_f32_e64 s[38:39], |v33|, s1
	v_and_b32_e32 v41, 0xffff0000, v41
	v_pk_mul_f32 v[26:27], v[26:27], v[40:41]
	v_cndmask_b32_e64 v33, v33, v61, s[38:39]
	v_cndmask_b32_e32 v61, 0, v229, vcc
	v_cmp_gt_f32_e32 vcc, s33, v69
	v_sub_f32_e32 v33, v33, v61
	v_add_f32_e32 v33, v60, v33
	v_cndmask_b32_e64 v70, 0, 32, vcc
	v_ldexp_f32 v69, v69, v70
	v_log_f32_e32 v69, v69
	v_sub_f32_e32 v33, -0.5, v33
	v_mul_f32_e32 v33, 0x3fb8aa3b, v33
	v_exp_f32_e32 v33, v33
	v_mul_f32_e32 v70, 0x3f317217, v69
	v_fma_f32 v70, v69, s2, -v70
	v_fmac_f32_e32 v70, 0x3377d1cf, v69
	v_fmac_f32_e32 v70, 0x3f317217, v69
	v_cmp_lt_f32_e64 s[38:39], |v69|, s1
	v_mul_f32_e32 v33, 0xbfb8aa3b, v33
	v_exp_f32_e32 v33, v33
	v_cndmask_b32_e64 v69, v69, v70, s[38:39]
	v_cndmask_b32_e32 v70, 0, v229, vcc
	v_sub_f32_e32 v69, v69, v70
	v_pk_add_f32 v[24:25], v[24:25], v[68:69]
	v_pk_mul_f32 v[60:61], v[176:177], v[148:149] op_sel_hi:[1,0]
	v_pk_mul_f32 v[24:25], v[66:67], v[24:25]
	v_pk_add_f32 v[62:63], v[32:33], 1.0 op_sel_hi:[1,0] neg_lo:[1,0] neg_hi:[1,0]
	v_add_f32_e32 v66, v24, v24
	v_mul_f32_e32 v66, 0x3fb8aa3b, v66
	v_exp_f32_e32 v66, v66
	v_pk_mul_f32 v[32:33], v[172:173], v[60:61]
	v_exp_f32_e32 v11, v11
	v_cvt_pk_bf16_f32 v32, v32, v33
	v_sub_f32_e32 v66, 1.0, v66
	v_max_f32_e32 v66, 0, v66
	v_cmp_gt_f32_e32 vcc, s4, v66
	v_mul_f32_e32 v67, 0x4f800000, v66
	v_add_f32_e32 v10, 1.0, v10
	v_cndmask_b32_e32 v66, v66, v67, vcc
	v_sqrt_f32_e32 v67, v66
	v_add_f32_e32 v11, 1.0, v11
	v_rcp_f32_e32 v10, v10
	v_rcp_f32_e32 v11, v11
	v_add_u32_e32 v68, -1, v67
	v_fma_f32 v69, -v68, v67, v66
	v_cmp_ge_f32_e64 s[38:39], 0, v69
	v_add_u32_e32 v69, 1, v67
	v_pk_mul_f32 v[10:11], v[10:11], s[6:7] op_sel_hi:[1,0]
	v_cndmask_b32_e64 v68, v67, v68, s[38:39]
	v_fma_f32 v67, -v69, v67, v66
	v_cmp_lt_f32_e64 s[38:39], 0, v67
	v_add_f32_e32 v6, v6, v50
	v_add_f32_e32 v7, v7, v51
	v_cndmask_b32_e64 v67, v68, v69, s[38:39]
	v_mul_f32_e32 v68, 0x37800000, v67
	v_cndmask_b32_e32 v67, v67, v68, vcc
	v_cmp_class_f32_e32 vcc, v66, v218
	v_mul_f32_e32 v6, 0xbfb8aa3b, v6
	v_mul_f32_e32 v7, 0xbfb8aa3b, v7
	v_cndmask_b32_e32 v66, v67, v66, vcc
	v_add_f32_e32 v67, v25, v25
	v_mul_f32_e32 v67, 0x3fb8aa3b, v67
	v_exp_f32_e32 v67, v67
	v_exp_f32_e32 v6, v6
	v_exp_f32_e32 v7, v7
	v_cvt_pk_bf16_f32 v0, v0, v1
	v_sub_f32_e32 v67, 1.0, v67
	v_max_f32_e32 v67, 0, v67
	v_cmp_gt_f32_e32 vcc, s4, v67
	v_mul_f32_e32 v68, 0x4f800000, v67
	v_add_f32_e32 v6, 1.0, v6
	v_cndmask_b32_e32 v67, v67, v68, vcc
	v_sqrt_f32_e32 v68, v67
	v_add_f32_e32 v7, 1.0, v7
	v_rcp_f32_e32 v6, v6
	v_rcp_f32_e32 v7, v7
	v_add_u32_e32 v69, -1, v68
	v_fma_f32 v70, -v69, v68, v67
	v_cmp_ge_f32_e64 s[38:39], 0, v70
	v_add_u32_e32 v70, 1, v68
	v_cvt_pk_bf16_f32 v1, v2, v3
	v_cndmask_b32_e64 v69, v68, v69, s[38:39]
	v_fma_f32 v68, -v70, v68, v67
	v_cmp_lt_f32_e64 s[38:39], 0, v68
	s_add_i32 s78, s78, s7
	s_cmpk_gt_i32 s78, 0x3ff
	v_cndmask_b32_e64 v68, v69, v70, s[38:39]
	v_mul_f32_e32 v69, 0x37800000, v68
	v_cndmask_b32_e32 v68, v68, v69, vcc
	v_cmp_class_f32_e32 vcc, v67, v218
	v_mul_f32_e64 v69, |v95|, s0
	v_exp_f32_e32 v69, v69
	v_cndmask_b32_e32 v67, v68, v67, vcc
	v_cmp_gt_f32_e32 vcc, s33, v34
	v_pk_mul_f32 v[28:29], v[66:67], v[28:29]
	v_add_f32_e32 v69, 1.0, v69
	v_cndmask_b32_e64 v65, 0, 32, vcc
	v_ldexp_f32 v34, v34, v65
	v_log_f32_e32 v34, v34
	s_nop 0
	v_mul_f32_e32 v65, 0x3f317217, v34
	v_fma_f32 v65, v34, s2, -v65
	v_fmac_f32_e32 v65, 0x3377d1cf, v34
	v_fmac_f32_e32 v65, 0x3f317217, v34
	v_cmp_lt_f32_e64 s[38:39], |v34|, s1
	s_nop 1
	v_cndmask_b32_e64 v34, v34, v65, s[38:39]
	v_cndmask_b32_e32 v65, 0, v229, vcc
	v_sub_f32_e32 v34, v34, v65
	v_mul_f32_e64 v65, |v94|, s0
	v_exp_f32_e32 v65, v65
	v_add_f32_e32 v34, v64, v34
	v_sub_f32_e32 v34, -0.5, v34
	v_mul_f32_e32 v34, 0x3fb8aa3b, v34
	v_add_f32_e32 v65, 1.0, v65
	v_cmp_gt_f32_e32 vcc, s33, v65
	v_exp_f32_e32 v34, v34
	s_nop 0
	v_cndmask_b32_e64 v66, 0, 32, vcc
	v_ldexp_f32 v65, v65, v66
	v_log_f32_e32 v65, v65
	v_mul_f32_e32 v34, 0xbfb8aa3b, v34
	v_exp_f32_e32 v64, v34
	v_max_f32_e64 v34, -v94, -v94
	v_mul_f32_e32 v66, 0x3f317217, v65
	v_fma_f32 v66, v65, s2, -v66
	v_fmac_f32_e32 v66, 0x3377d1cf, v65
	v_fmac_f32_e32 v66, 0x3f317217, v65
	v_cmp_lt_f32_e64 s[38:39], |v65|, s1
	v_max_f32_e32 v34, 0, v34
	s_nop 0
	v_cndmask_b32_e64 v65, v65, v66, s[38:39]
	v_cndmask_b32_e32 v66, 0, v229, vcc
	v_sub_f32_e32 v68, v65, v66
	v_max_f32_e64 v65, -v35, 0
	v_mul_f32_e64 v35, |v35|, s0
	v_exp_f32_e32 v35, v35
	s_nop 0
	v_add_f32_e32 v35, 1.0, v35
	v_cmp_gt_f32_e32 vcc, s33, v35
	s_nop 1
	v_cndmask_b32_e64 v66, 0, 32, vcc
	v_ldexp_f32 v35, v35, v66
	v_log_f32_e32 v35, v35
; __device__ __forceinline__ float sigmoidf_(float x) { return __builtin_amdgcn_rcpf(1.f + __expf(-x)); }
; __device__ __forceinline__ float softplus_fast(float x) { return fmaxf(x, 0.f) + __logf(1.f + __expf(-fabsf(x))); }
; __device__ __forceinline__ void prep_unit(CP p, int l, int u, char* smem) {
;     ...
;       for (int j = 0; j < 4; ++j) {
;         const int x = mf * 4 + j;
;         const float wv = w0_[j] + accw[mf][j];
;         const float w = -softplus_fast(-wv) - 0.5f;
;         omw[j] = 1.f - __expf(-__expf(w));
;         kn[j] = kkv[x] * inv;
;         bb[j] = kn[j] * avv[x];
;         const float rr = sigmoidf_(accr[mf][j] + ba_[j]), ii = sigmoidf_(acci[mf][j] + bx_[j]);
;         la[j] = -8.f * rr * softplus_fast(-lam_[j]);
;         uu[j] = sqrtf(fmaxf(1.f - __expf(2.f * la[j]), 0.f)) * (ii * xc_[j]);
;       }
;       bf16_t* o = RW + row * 1536 + c;
;       *reinterpret_cast<uint2*>(o) = make_uint2(pack2(omw[0], omw[1]), pack2(omw[2], omw[3]));
;       *reinterpret_cast<uint2*>(o + 256) = make_uint2(pack2(kn[0], kn[1]), pack2(kn[2], kn[3]));
;       *reinterpret_cast<uint2*>(o + 512) = make_uint2(pack2(bb[0], bb[1]), pack2(bb[2], bb[3]));
;       *reinterpret_cast<uint2*>(o + 768) = make_uint2(pack2(kpv[mf * 4], kpv[mf * 4 + 1]), pack2(kpv[mf * 4 + 2], kpv[mf * 4 + 3]));
;       *reinterpret_cast<uint2*>(o + 1024) = make_uint2(pack2(rv[mf * 4], rv[mf * 4 + 1]), pack2(rv[mf * 4 + 2], rv[mf * 4 + 3]));
;       *reinterpret_cast<uint2*>(RG + row * 256 + c) = make_uint2(pack2(accg[mf][0], accg[mf][1]), pack2(accg[mf][2], accg[mf][3]));
;       *reinterpret_cast<uint2*>(LR + row * 512 + c) = make_uint2(pack2(la[0], la[1]), pack2(la[2], la[3]));
;       *reinterpret_cast<uint2*>(LR + row * 512 + 256 + c) = make_uint2(pack2(uu[0], uu[1]), pack2(uu[2], uu[3]));
	s_nop 0
	v_mul_f32_e32 v66, 0x3f317217, v35
	v_fma_f32 v66, v35, s2, -v66
	v_fmac_f32_e32 v66, 0x3377d1cf, v35
	v_fmac_f32_e32 v66, 0x3f317217, v35
	v_cmp_lt_f32_e64 s[38:39], |v35|, s1
	s_nop 1
	v_cndmask_b32_e64 v35, v35, v66, s[38:39]
	v_cndmask_b32_e32 v66, 0, v229, vcc
	v_cmp_gt_f32_e32 vcc, s33, v69
	v_sub_f32_e32 v35, v35, v66
	v_add_f32_e32 v35, v65, v35
	v_cndmask_b32_e64 v72, 0, 32, vcc
	v_ldexp_f32 v69, v69, v72
	v_log_f32_e32 v69, v69
	v_sub_f32_e32 v35, -0.5, v35
	v_mul_f32_e32 v35, 0x3fb8aa3b, v35
	v_exp_f32_e32 v35, v35
	v_mul_f32_e32 v72, 0x3f317217, v69
	v_fma_f32 v72, v69, s2, -v72
	v_fmac_f32_e32 v72, 0x3377d1cf, v69
	v_mul_f32_e32 v35, 0xbfb8aa3b, v35
	v_fmac_f32_e32 v72, 0x3f317217, v69
	v_cmp_lt_f32_e64 s[38:39], |v69|, s1
	v_exp_f32_e32 v65, v35
	v_max_f32_e64 v35, -v95, -v95
	v_cndmask_b32_e64 v69, v69, v72, s[38:39]
	v_cndmask_b32_e32 v72, 0, v229, vcc
	v_max_f32_e32 v35, 0, v35
	v_sub_f32_e32 v69, v69, v72
	v_pk_add_f32 v[34:35], v[34:35], v[68:69]
	v_pk_mul_f32 v[66:67], v[170:171], v[148:149] op_sel_hi:[1,0]
	v_pk_mul_f32 v[30:31], v[30:31], v[34:35]
	v_pk_add_f32 v[70:71], v[64:65], 1.0 op_sel_hi:[1,0] neg_lo:[1,0] neg_hi:[1,0]
	v_add_f32_e32 v34, v30, v30
	v_mul_f32_e32 v34, 0x3fb8aa3b, v34
	v_exp_f32_e32 v34, v34
	v_pk_mul_f32 v[64:65], v[168:169], v[66:67]
	v_sub_f32_e32 v34, 1.0, v34
	v_max_f32_e32 v34, 0, v34
	v_cmp_gt_f32_e32 vcc, s4, v34
	v_mul_f32_e32 v35, 0x4f800000, v34
	v_cvt_pk_bf16_f32 v33, v64, v65
	v_cndmask_b32_e32 v34, v34, v35, vcc
	v_sqrt_f32_e32 v35, v34
	global_store_dwordx2 v[80:81], v[32:33], off offset:1088
	v_cvt_pk_bf16_f32 v32, v160, v161
	v_cvt_pk_bf16_f32 v33, v164, v165
	v_add_u32_e32 v68, -1, v35
	v_fma_f32 v69, -v68, v35, v34
	v_cmp_ge_f32_e64 s[38:39], 0, v69
	v_add_u32_e32 v69, 1, v35
	global_store_dwordx2 v[80:81], v[32:33], off offset:1600
	v_cndmask_b32_e64 v68, v35, v68, s[38:39]
	v_fma_f32 v35, -v69, v35, v34
	v_cmp_lt_f32_e64 s[38:39], 0, v35
	v_cvt_pk_bf16_f32 v32, v36, v37
	v_cvt_pk_bf16_f32 v33, v38, v39
	v_cndmask_b32_e64 v35, v68, v69, s[38:39]
	v_mul_f32_e32 v68, 0x37800000, v35
	v_cndmask_b32_e32 v35, v35, v68, vcc
	v_cmp_class_f32_e32 vcc, v34, v218
	global_store_dwordx2 v[80:81], v[32:33], off offset:2112
	s_waitcnt vmcnt(19)
	v_mul_f32_e64 v33, |v47|, s0
	v_cndmask_b32_e32 v34, v35, v34, vcc
	v_add_f32_e32 v35, v31, v31
	v_mul_f32_e32 v35, 0x3fb8aa3b, v35
	v_exp_f32_e32 v35, v35
	v_exp_f32_e32 v33, v33
	v_sub_f32_e32 v35, 1.0, v35
	v_max_f32_e32 v35, 0, v35
	v_cmp_gt_f32_e32 vcc, s4, v35
	v_mul_f32_e32 v68, 0x4f800000, v35
	v_add_f32_e32 v33, 1.0, v33
	v_cndmask_b32_e32 v35, v35, v68, vcc
	v_sqrt_f32_e32 v68, v35
	s_nop 0
	v_add_u32_e32 v69, -1, v68
	v_fma_f32 v72, -v69, v68, v35
	v_cmp_ge_f32_e64 s[38:39], 0, v72
	v_add_u32_e32 v72, 1, v68
	s_nop 0
	v_cndmask_b32_e64 v69, v68, v69, s[38:39]
	v_fma_f32 v68, -v72, v68, v35
	v_cmp_lt_f32_e64 s[38:39], 0, v68
	s_nop 1
	v_cndmask_b32_e64 v68, v69, v72, s[38:39]
	v_mul_f32_e32 v69, 0x37800000, v68
	v_cndmask_b32_e32 v68, v68, v69, vcc
	v_cmp_class_f32_e32 vcc, v35, v218
	s_nop 1
	v_cndmask_b32_e32 v35, v68, v35, vcc
	v_cmp_gt_f32_e32 vcc, s33, v12
	v_pk_mul_f32 v[26:27], v[34:35], v[26:27]
	v_cvt_pk_bf16_f32 v34, v62, v63
	v_cndmask_b32_e64 v19, 0, 32, vcc
	v_ldexp_f32 v12, v12, v19
	v_log_f32_e32 v12, v12
	v_cvt_pk_bf16_f32 v35, v70, v71
	global_store_dwordx2 v[80:81], v[34:35], off offset:64
	v_cvt_pk_bf16_f32 v34, v60, v61
	v_mul_f32_e32 v19, 0x3f317217, v12
	v_fma_f32 v19, v12, s2, -v19
	v_fmac_f32_e32 v19, 0x3377d1cf, v12
	v_fmac_f32_e32 v19, 0x3f317217, v12
	v_cmp_lt_f32_e64 s[38:39], |v12|, s1
	v_cvt_pk_bf16_f32 v35, v66, v67
	global_store_dwordx2 v[80:81], v[34:35], off offset:576
	v_cndmask_b32_e64 v12, v12, v19, s[38:39]
	v_cndmask_b32_e32 v19, 0, v229, vcc
	v_sub_f32_e32 v12, v12, v19
	v_add_f32_e32 v12, v18, v12
	v_mul_f32_e64 v18, |v44|, s0
	v_exp_f32_e32 v18, v18
	global_store_dwordx2 v[78:79], v[16:17], off offset:64
	v_cvt_pk_bf16_f32 v17, v30, v31
	v_mul_f32_e64 v31, |v45|, s0
	v_add_f32_e32 v18, 1.0, v18
	v_cmp_gt_f32_e32 vcc, s33, v18
	v_exp_f32_e32 v31, v31
	v_cvt_pk_bf16_f32 v16, v24, v25
	v_cndmask_b32_e64 v19, 0, 32, vcc
	v_ldexp_f32 v18, v18, v19
	v_log_f32_e32 v18, v18
	v_add_f32_e32 v31, 1.0, v31
	global_store_dwordx2 v[76:77], v[16:17], off offset:64
	v_cvt_pk_bf16_f32 v16, v28, v29
	v_mul_f32_e32 v19, 0x3f317217, v18
	v_fma_f32 v19, v18, s2, -v19
	v_fmac_f32_e32 v19, 0x3377d1cf, v18
	v_fmac_f32_e32 v19, 0x3f317217, v18
	v_cmp_lt_f32_e64 s[38:39], |v18|, s1
	v_rcp_f32_e32 v28, v8
	v_rcp_f32_e32 v29, v9
	v_cndmask_b32_e64 v18, v18, v19, s[38:39]
	v_cndmask_b32_e32 v19, 0, v229, vcc
	v_sub_f32_e32 v30, v18, v19
	v_max_f32_e64 v18, -v13, 0
	v_mul_f32_e64 v13, |v13|, s0
	v_exp_f32_e32 v13, v13
	v_rcp_f32_e32 v8, v4
	v_max_f32_e64 v4, -v44, -v44
	v_rcp_f32_e32 v9, v5
	v_add_f32_e32 v13, 1.0, v13
	v_cmp_gt_f32_e32 vcc, s33, v13
	v_max_f32_e64 v5, -v45, -v45
	v_max_f32_e32 v4, 0, v4
	v_cndmask_b32_e64 v19, 0, 32, vcc
	v_ldexp_f32 v13, v13, v19
	v_log_f32_e32 v13, v13
	v_max_f32_e32 v5, 0, v5
	v_pk_mul_f32 v[28:29], v[28:29], s[6:7] op_sel_hi:[1,0]
	v_cvt_pk_bf16_f32 v17, v26, v27
	v_mul_f32_e32 v19, 0x3f317217, v13
	v_fma_f32 v19, v13, s2, -v19
	v_fmac_f32_e32 v19, 0x3377d1cf, v13
	v_fmac_f32_e32 v19, 0x3f317217, v13
	v_cmp_lt_f32_e64 s[38:39], |v13|, s1
	v_lshlrev_b32_e32 v26, 16, v42
	v_and_b32_e32 v27, 0xffff0000, v42
	v_cndmask_b32_e64 v13, v13, v19, s[38:39]
	v_cndmask_b32_e32 v19, 0, v229, vcc
	v_cmp_gt_f32_e32 vcc, s33, v31
	v_pk_mul_f32 v[8:9], v[8:9], v[26:27]
	v_max_f32_e64 v26, -v14, 0
	v_cndmask_b32_e64 v32, 0, 32, vcc
	v_ldexp_f32 v31, v31, v32
	v_log_f32_e32 v31, v31
; __device__ __forceinline__ float sigmoidf_(float x) { return __builtin_amdgcn_rcpf(1.f + __expf(-x)); }
; __device__ __forceinline__ float softplus_fast(float x) { return fmaxf(x, 0.f) + __logf(1.f + __expf(-fabsf(x))); }
; __device__ __forceinline__ void prep_unit(CP p, int l, int u, char* smem) {
;     ...
;       for (int j = 0; j < 4; ++j) {
;         const int x = mf * 4 + j;
;         const float wv = w0_[j] + accw[mf][j];
;         const float w = -softplus_fast(-wv) - 0.5f;
;         omw[j] = 1.f - __expf(-__expf(w));
;         kn[j] = kkv[x] * inv;
;         bb[j] = kn[j] * avv[x];
;         const float rr = sigmoidf_(accr[mf][j] + ba_[j]), ii = sigmoidf_(acci[mf][j] + bx_[j]);
;         la[j] = -8.f * rr * softplus_fast(-lam_[j]);
;         uu[j] = sqrtf(fmaxf(1.f - __expf(2.f * la[j]), 0.f)) * (ii * xc_[j]);
	v_mul_f32_e64 v14, |v14|, s0
	v_exp_f32_e32 v14, v14
	v_sub_f32_e32 v13, v13, v19
	v_mul_f32_e32 v32, 0x3f317217, v31
	v_fma_f32 v32, v31, s2, -v32
	v_fmac_f32_e32 v32, 0x3377d1cf, v31
	v_fmac_f32_e32 v32, 0x3f317217, v31
	v_cmp_lt_f32_e64 s[38:39], |v31|, s1
	v_add_f32_e32 v14, 1.0, v14
	v_add_f32_e32 v13, v18, v13
	v_cndmask_b32_e64 v31, v31, v32, s[38:39]
	v_cndmask_b32_e32 v32, 0, v229, vcc
	v_sub_f32_e32 v31, v31, v32
	v_pk_add_f32 v[4:5], v[4:5], v[30:31]
	v_sub_f32_e32 v12, -0.5, v12
	v_pk_mul_f32 v[4:5], v[28:29], v[4:5]
	v_sub_f32_e32 v13, -0.5, v13
	v_add_f32_e32 v28, v4, v4
	v_mul_f32_e32 v28, 0x3fb8aa3b, v28
	v_exp_f32_e32 v28, v28
	v_mul_f32_e32 v12, 0x3fb8aa3b, v12
	v_mul_f32_e32 v13, 0x3fb8aa3b, v13
	v_exp_f32_e32 v12, v12
	v_sub_f32_e32 v28, 1.0, v28
	v_max_f32_e32 v28, 0, v28
	v_cmp_gt_f32_e32 vcc, s4, v28
	v_mul_f32_e32 v29, 0x4f800000, v28
	v_exp_f32_e32 v13, v13
	v_cndmask_b32_e32 v28, v28, v29, vcc
	v_sqrt_f32_e32 v29, v28
	v_mul_f32_e32 v12, 0xbfb8aa3b, v12
	v_mul_f32_e32 v13, 0xbfb8aa3b, v13
	v_exp_f32_e32 v12, v12
	v_add_u32_e32 v30, -1, v29
	v_fma_f32 v31, -v30, v29, v28
	v_cmp_ge_f32_e64 s[38:39], 0, v31
	v_add_u32_e32 v31, 1, v29
	v_exp_f32_e32 v13, v13
	v_cndmask_b32_e64 v30, v29, v30, s[38:39]
	v_fma_f32 v29, -v31, v29, v28
	v_cmp_lt_f32_e64 s[38:39], 0, v29
	v_pk_mul_f32 v[18:19], v[166:167], v[148:149] op_sel_hi:[1,0]
	global_store_dwordx2 v[76:77], v[16:17], off offset:576
	v_cndmask_b32_e64 v29, v30, v31, s[38:39]
	v_mul_f32_e32 v30, 0x37800000, v29
	v_cndmask_b32_e32 v29, v29, v30, vcc
	v_cmp_class_f32_e32 vcc, v28, v218
	v_lshlrev_b32_e32 v16, 16, v43
	v_and_b32_e32 v17, 0xffff0000, v43
	v_cndmask_b32_e32 v28, v29, v28, vcc
	v_add_f32_e32 v29, v5, v5
	v_mul_f32_e32 v29, 0x3fb8aa3b, v29
	v_exp_f32_e32 v29, v29
	v_pk_add_f32 v[24:25], v[12:13], 1.0 op_sel_hi:[1,0] neg_lo:[1,0] neg_hi:[1,0]
	v_pk_mul_f32 v[12:13], v[162:163], v[18:19]
	v_pk_mul_f32 v[6:7], v[6:7], v[16:17]
	v_sub_f32_e32 v29, 1.0, v29
	v_max_f32_e32 v29, 0, v29
	v_cmp_gt_f32_e32 vcc, s4, v29
	v_mul_f32_e32 v30, 0x4f800000, v29
	v_cvt_pk_bf16_f32 v12, v12, v13
	v_cndmask_b32_e32 v29, v29, v30, vcc
	v_sqrt_f32_e32 v30, v29
	s_mov_b32 s6, s7
	v_add_u32_e32 v31, -1, v30
	v_fma_f32 v32, -v31, v30, v29
	v_cmp_ge_f32_e64 s[38:39], 0, v32
	v_add_u32_e32 v32, 1, v30
	s_nop 0
	v_cndmask_b32_e64 v31, v30, v31, s[38:39]
	v_fma_f32 v30, -v32, v30, v29
	v_cmp_lt_f32_e64 s[38:39], 0, v30
	s_nop 1
	v_cndmask_b32_e64 v30, v31, v32, s[38:39]
	v_mul_f32_e32 v31, 0x37800000, v30
	v_cndmask_b32_e32 v30, v30, v31, vcc
	v_cmp_class_f32_e32 vcc, v29, v218
	s_nop 1
	v_cndmask_b32_e32 v29, v30, v29, vcc
	v_cmp_gt_f32_e32 vcc, s33, v14
	v_pk_mul_f32 v[8:9], v[28:29], v[8:9]
	s_nop 0
	v_cndmask_b32_e64 v27, 0, 32, vcc
	v_ldexp_f32 v14, v14, v27
	v_log_f32_e32 v14, v14
	s_nop 0
	v_mul_f32_e32 v27, 0x3f317217, v14
	v_fma_f32 v27, v14, s2, -v27
	v_fmac_f32_e32 v27, 0x3377d1cf, v14
	v_fmac_f32_e32 v27, 0x3f317217, v14
	v_cmp_lt_f32_e64 s[38:39], |v14|, s1
	s_nop 1
	v_cndmask_b32_e64 v14, v14, v27, s[38:39]
	v_cndmask_b32_e32 v27, 0, v229, vcc
	v_sub_f32_e32 v14, v14, v27
	v_mul_f32_e64 v27, |v46|, s0
	v_exp_f32_e32 v27, v27
	v_add_f32_e32 v14, v26, v14
	v_sub_f32_e32 v14, -0.5, v14
	v_mul_f32_e32 v14, 0x3fb8aa3b, v14
	v_add_f32_e32 v27, 1.0, v27
	v_cmp_gt_f32_e32 vcc, s33, v27
	v_exp_f32_e32 v14, v14
	s_nop 0
	v_cndmask_b32_e64 v28, 0, 32, vcc
	v_ldexp_f32 v27, v27, v28
	v_log_f32_e32 v27, v27
	v_mul_f32_e32 v14, 0xbfb8aa3b, v14
	v_exp_f32_e32 v26, v14
	v_max_f32_e64 v14, -v46, -v46
	v_mul_f32_e32 v28, 0x3f317217, v27
	v_fma_f32 v28, v27, s2, -v28
	v_fmac_f32_e32 v28, 0x3377d1cf, v27
	v_fmac_f32_e32 v28, 0x3f317217, v27
	v_cmp_lt_f32_e64 s[38:39], |v27|, s1
	v_max_f32_e32 v14, 0, v14
	s_nop 0
	v_cndmask_b32_e64 v27, v27, v28, s[38:39]
	v_cndmask_b32_e32 v28, 0, v229, vcc
	v_sub_f32_e32 v32, v27, v28
; __device__ __forceinline__ float sigmoidf_(float x) { return __builtin_amdgcn_rcpf(1.f + __expf(-x)); }
; __device__ __forceinline__ float softplus_fast(float x) { return fmaxf(x, 0.f) + __logf(1.f + __expf(-fabsf(x))); }
; __device__ __forceinline__ void prep_unit(CP p, int l, int u, char* smem) {
;     ...
;       for (int j = 0; j < 4; ++j) {
;         const int x = mf * 4 + j;
;         const float wv = w0_[j] + accw[mf][j];
;         const float w = -softplus_fast(-wv) - 0.5f;
;         omw[j] = 1.f - __expf(-__expf(w));
;         kn[j] = kkv[x] * inv;
;         bb[j] = kn[j] * avv[x];
;         const float rr = sigmoidf_(accr[mf][j] + ba_[j]), ii = sigmoidf_(acci[mf][j] + bx_[j]);
;         la[j] = -8.f * rr * softplus_fast(-lam_[j]);
;         uu[j] = sqrtf(fmaxf(1.f - __expf(2.f * la[j]), 0.f)) * (ii * xc_[j]);
;       }
;       bf16_t* o = RW + row * 1536 + c;
;       *reinterpret_cast<uint2*>(o) = make_uint2(pack2(omw[0], omw[1]), pack2(omw[2], omw[3]));
;       *reinterpret_cast<uint2*>(o + 256) = make_uint2(pack2(kn[0], kn[1]), pack2(kn[2], kn[3]));
;       *reinterpret_cast<uint2*>(o + 512) = make_uint2(pack2(bb[0], bb[1]), pack2(bb[2], bb[3]));
;       *reinterpret_cast<uint2*>(o + 768) = make_uint2(pack2(kpv[mf * 4], kpv[mf * 4 + 1]), pack2(kpv[mf * 4 + 2], kpv[mf * 4 + 3]));
;       *reinterpret_cast<uint2*>(o + 1024) = make_uint2(pack2(rv[mf * 4], rv[mf * 4 + 1]), pack2(rv[mf * 4 + 2], rv[mf * 4 + 3]));
;       *reinterpret_cast<uint2*>(RG + row * 256 + c) = make_uint2(pack2(accg[mf][0], accg[mf][1]), pack2(accg[mf][2], accg[mf][3]));
;       *reinterpret_cast<uint2*>(LR + row * 512 + c) = make_uint2(pack2(la[0], la[1]), pack2(la[2], la[3]));
;       *reinterpret_cast<uint2*>(LR + row * 512 + 256 + c) = make_uint2(pack2(uu[0], uu[1]), pack2(uu[2], uu[3]));
;     }
	v_max_f32_e64 v27, -v15, 0
	v_mul_f32_e64 v15, |v15|, s0
	v_exp_f32_e32 v15, v15
	s_nop 0
	v_add_f32_e32 v15, 1.0, v15
	v_cmp_gt_f32_e32 vcc, s33, v15
	s_nop 1
	v_cndmask_b32_e64 v28, 0, 32, vcc
	v_ldexp_f32 v15, v15, v28
	v_log_f32_e32 v15, v15
	s_nop 0
	v_mul_f32_e32 v28, 0x3f317217, v15
	v_fma_f32 v28, v15, s2, -v28
	v_fmac_f32_e32 v28, 0x3377d1cf, v15
	v_fmac_f32_e32 v28, 0x3f317217, v15
	v_cmp_lt_f32_e64 s[38:39], |v15|, s1
	s_nop 1
	v_cndmask_b32_e64 v15, v15, v28, s[38:39]
	v_cndmask_b32_e32 v28, 0, v229, vcc
	v_cmp_gt_f32_e32 vcc, s33, v33
	v_sub_f32_e32 v15, v15, v28
	v_add_f32_e32 v15, v27, v15
	v_cndmask_b32_e64 v34, 0, 32, vcc
	v_ldexp_f32 v33, v33, v34
	v_log_f32_e32 v33, v33
	v_sub_f32_e32 v15, -0.5, v15
	v_mul_f32_e32 v15, 0x3fb8aa3b, v15
	v_exp_f32_e32 v15, v15
	v_mul_f32_e32 v34, 0x3f317217, v33
	v_fma_f32 v34, v33, s2, -v34
	v_fmac_f32_e32 v34, 0x3377d1cf, v33
	v_mul_f32_e32 v15, 0xbfb8aa3b, v15
	v_fmac_f32_e32 v34, 0x3f317217, v33
	v_cmp_lt_f32_e64 s[38:39], |v33|, s1
	v_exp_f32_e32 v27, v15
	v_max_f32_e64 v15, -v47, -v47
	v_cndmask_b32_e64 v33, v33, v34, s[38:39]
	v_cndmask_b32_e32 v34, 0, v229, vcc
	v_max_f32_e32 v15, 0, v15
	v_sub_f32_e32 v33, v33, v34
	v_pk_add_f32 v[14:15], v[14:15], v[32:33]
	v_pk_mul_f32 v[28:29], v[158:159], v[148:149] op_sel_hi:[1,0]
	v_pk_mul_f32 v[10:11], v[10:11], v[14:15]
	v_pk_add_f32 v[30:31], v[26:27], 1.0 op_sel_hi:[1,0] neg_lo:[1,0] neg_hi:[1,0]
	v_add_f32_e32 v14, v10, v10
	v_mul_f32_e32 v14, 0x3fb8aa3b, v14
	v_exp_f32_e32 v14, v14
	v_pk_mul_f32 v[26:27], v[156:157], v[28:29]
	v_sub_f32_e32 v14, 1.0, v14
	v_max_f32_e32 v14, 0, v14
	v_cmp_gt_f32_e32 vcc, s4, v14
	v_mul_f32_e32 v15, 0x4f800000, v14
	v_cvt_pk_bf16_f32 v13, v26, v27
	v_cndmask_b32_e32 v14, v14, v15, vcc
	v_sqrt_f32_e32 v15, v14
	global_store_dwordx2 v[80:81], v[12:13], off offset:1120
	v_cvt_pk_bf16_f32 v12, v152, v153
	v_cvt_pk_bf16_f32 v13, v154, v155
	v_add_u32_e32 v32, -1, v15
	v_fma_f32 v33, -v32, v15, v14
	v_cmp_ge_f32_e64 s[38:39], 0, v33
	v_add_u32_e32 v33, 1, v15
	global_store_dwordx2 v[80:81], v[12:13], off offset:1632
	v_cndmask_b32_e64 v32, v15, v32, s[38:39]
	v_fma_f32 v15, -v33, v15, v14
	v_cmp_lt_f32_e64 s[38:39], 0, v15
	v_cvt_pk_bf16_f32 v12, v20, v21
	v_cvt_pk_bf16_f32 v13, v22, v23
	v_cndmask_b32_e64 v15, v32, v33, s[38:39]
	v_mul_f32_e32 v32, 0x37800000, v15
	v_cndmask_b32_e32 v15, v15, v32, vcc
	v_cmp_class_f32_e32 vcc, v14, v218
	global_store_dwordx2 v[80:81], v[12:13], off offset:2144
	s_nop 0
	v_cndmask_b32_e32 v14, v15, v14, vcc
	v_add_f32_e32 v15, v11, v11
	v_mul_f32_e32 v15, 0x3fb8aa3b, v15
	v_exp_f32_e32 v15, v15
	s_nop 0
	v_sub_f32_e32 v15, 1.0, v15
	v_max_f32_e32 v15, 0, v15
	v_cmp_gt_f32_e32 vcc, s4, v15
	v_mul_f32_e32 v32, 0x4f800000, v15
	s_nop 0
	v_cndmask_b32_e32 v15, v15, v32, vcc
	v_sqrt_f32_e32 v32, v15
	s_nop 0
	v_add_u32_e32 v33, -1, v32
	v_fma_f32 v34, -v33, v32, v15
	v_cmp_ge_f32_e64 s[38:39], 0, v34
	v_add_u32_e32 v34, 1, v32
	s_nop 0
	v_cndmask_b32_e64 v33, v32, v33, s[38:39]
	v_fma_f32 v32, -v34, v32, v15
	v_cmp_lt_f32_e64 s[38:39], 0, v32
	s_nop 1
	v_cndmask_b32_e64 v32, v33, v34, s[38:39]
	v_mul_f32_e32 v33, 0x37800000, v32
	v_cndmask_b32_e32 v32, v32, v33, vcc
	v_cmp_class_f32_e32 vcc, v15, v218
	s_nop 1
	v_cndmask_b32_e32 v15, v32, v15, vcc
	v_pk_mul_f32 v[6:7], v[14:15], v[6:7]
	v_cvt_pk_bf16_f32 v14, v24, v25
	v_cvt_pk_bf16_f32 v15, v30, v31
	global_store_dwordx2 v[80:81], v[14:15], off offset:96
	v_cvt_pk_bf16_f32 v14, v18, v19
	v_cvt_pk_bf16_f32 v15, v28, v29
	global_store_dwordx2 v[80:81], v[14:15], off offset:608
	global_store_dwordx2 v[78:79], v[0:1], off offset:96
	v_cvt_pk_bf16_f32 v0, v4, v5
	v_cvt_pk_bf16_f32 v1, v10, v11
	global_store_dwordx2 v[76:77], v[0:1], off offset:96
	v_cvt_pk_bf16_f32 v0, v8, v9
	v_cvt_pk_bf16_f32 v1, v6, v7
	global_store_dwordx2 v[76:77], v[0:1], off offset:608
	s_cbranch_scc1 .LBB0_858

; __device__ __forceinline__ void run_phase(CP p, int ph, char* smem_full) {
;     ...
;       for (int u = vb; u < NB * 129; u += NVB) prep_unit(p, l, u, smem);
;     } break;
;     case 3: {
;       for (int u = vb; u < 320; u += NVB) {
;         if (u < 128) { for (int rr_ = 0; rr_ < ((SCAN_REP >> 0) & 1) + 1; ++rr_) rwkv_scan_unit(p, u, smem); }
;         else if (u < 256) { for (int rr_ = 0; rr_ < ((SCAN_REP >> 1) & 1) + 1; ++rr_) ssd_scan_unit(p, l, u - 128, smem); }
;         else if (u < 272) ret_mfma_unit(p, l, u - 256, smem);
;         else if (u < 288) { }
;         else if (u < 320) { for (int rr_ = 0; rr_ < ((SCAN_REP >> 3) & 1) + 1; ++rr_) lru_scan_unit(p, u - 288, smem); }
.LBB0_858:
	s_cmp_eq_u32 s55, 3
	s_cbranch_scc0 .Ltail_nopub
	s_waitcnt vmcnt(0) lgkmcnt(0)
	buffer_wbl2 sc1
	s_waitcnt vmcnt(0)
	s_mov_b64 s[2:3], exec
	s_mov_b64 exec, 1
	v_mov_b32_e32 v0, 1
	global_atomic_add v149, v0, s[52:53]
	s_mov_b64 exec, s[2:3]
	s_waitcnt vmcnt(0)
